# previous best plus hand-written FFN conv+gelu sample-row section (all taps of a row loaded together, next row prefetched)
# baseline (speedup 1.0000x reference)
; __device__ __forceinline__ u32x4 pack8(const float (&f)[8]) { u32x4 w; w.x = pk2(f[0], f[1]); w.y = pk2(f[2], f[3]); w.z = pk2(f[4], f[5]); w.w = pk2(f[6], f[7]); return w; }
; __device__ __forceinline__ float gelu_tanh(float x) { const float y = 1.5957691216f * (x + 0.044715f * x * x * x); return x * __builtin_amdgcn_rcpf(1.0f + __expf(-y)); }
; __device__ __forceinline__ void phase_ffnconv(const Params& p) {
;     ...
;     if (gt < 170 * NCH) {
;         const int c = gt % NCH, slot = gt / NCH, j0 = 8 * c, colg = (j0 >> 7) * 256 + (j0 & 127);
;         float wg[3][8], wv[3][8], bg[8], bv[8];
; #pragma unroll
;         for (int k = 0; k < 3; ++k) { ld8f(p.in[I_WFCONV] + (size_t)k * 2 * DFF + j0, wg[k]); ld8f(p.in[I_WFCONV] + (size_t)k * 2 * DFF + DFF + j0, wv[k]); }
;         ld8f(p.in[I_BFCONV] + j0, bg); ld8f(p.in[I_BFCONV] + DFF + j0, bv);
;         for (int rs = slot; rs < 1024; rs += 170) {
;             const int row = MPROMPT + rs, t = rs & 7, b = rs >> 3;
;             float xg[3][8], xv[3][8];
; #pragma unroll
;             for (int k = 0; k < 3; ++k) { const int tt = t - 2 + k;
;                 if (tt >= 0) { unpack8(*(const u32x4*)(UP + (size_t)(row - 2 + k) * 2 * DFF + colg), xg[k]); unpack8(*(const u32x4*)(UP + (size_t)(row - 2 + k) * 2 * DFF + colg + 128), xv[k]); }
;                 else { const float* sp = p.in[I_SFCONV] + ((size_t)b * 2 + (2 + tt)) * 2 * DFF; ld8f(sp + j0, xg[k]); ld8f(sp + DFF + j0, xv[k]); } }
;             float f[8];
; #pragma unroll
;             for (int e = 0; e < 8; ++e) { const float cg_ = bg[e] + xg[0][e] * wg[0][e] + xg[1][e] * wg[1][e] + xg[2][e] * wg[2][e];
;                 const float cv_ = bv[e] + xv[0][e] * wv[0][e] + xv[1][e] * wv[1][e] + xv[2][e] * wv[2][e]; f[e] = gelu_tanh(cg_) * cv_; }
;             *(u32x4*)(F + (size_t)row * DFF + j0) = pack8(f);
;         }
;     }
.LBB0_1296:
	s_or_b64 exec, exec, s[8:9]
	v_readfirstlane_b32 s14, v220
	s_lshr_b32 s15, s14, 8
	s_mul_i32 s15, s15, 0xaaab
	s_lshr_b32 s14, s15, 17
	s_cmp_ge_u32 s14, 0xaa
	s_cbranch_scc1 .Lffn_done
	v_readlane_b32 s8, v254, 15
	v_readlane_b32 s9, v254, 16
	v_readlane_b32 s10, v254, 41
	v_readlane_b32 s11, v254, 42
	v_readlane_b32 s12, v254, 43
	v_readlane_b32 s13, v254, 44
	s_mul_i32 s15, s14, 0x300
	v_subrev_u32_e32 v186, s15, v220
	v_lshlrev_b32_e32 v190, 5, v186
	v_lshlrev_b32_e32 v189, 4, v186
	v_add_u32_e32 v188, 0x6000, v190
	v_lshrrev_b32_e32 v187, 4, v186
	v_lshlrev_b32_e32 v187, 9, v187
	v_and_b32_e32 v191, 15, v186
	v_lshl_or_b32 v186, v191, 4, v187
	s_add_u32 s4, s84, 0x19d00000
	s_addc_u32 s5, s85, 0
	s_add_u32 s6, s84, 0x13d00000
	s_addc_u32 s7, s85, 0
	global_load_dwordx4 v[0:3], v190, s[10:11]
	global_load_dwordx4 v[4:7], v190, s[10:11] offset:16
	s_add_u32 s10, s10, 0x6000
	s_addc_u32 s11, s11, 0
	global_load_dwordx4 v[8:11], v190, s[10:11]
	global_load_dwordx4 v[12:15], v190, s[10:11] offset:16
	s_add_u32 s10, s10, 0x6000
	s_addc_u32 s11, s11, 0
	global_load_dwordx4 v[16:19], v190, s[10:11]
	global_load_dwordx4 v[20:23], v190, s[10:11] offset:16
	s_add_u32 s10, s10, 0x6000
	s_addc_u32 s11, s11, 0
	global_load_dwordx4 v[24:27], v190, s[10:11]
	global_load_dwordx4 v[28:31], v190, s[10:11] offset:16
	s_add_u32 s10, s10, 0x6000
	s_addc_u32 s11, s11, 0
	global_load_dwordx4 v[32:35], v190, s[10:11]
	global_load_dwordx4 v[36:39], v190, s[10:11] offset:16
	s_add_u32 s10, s10, 0x6000
	s_addc_u32 s11, s11, 0
	global_load_dwordx4 v[40:43], v190, s[10:11]
	global_load_dwordx4 v[44:47], v190, s[10:11] offset:16
	global_load_dwordx4 v[48:51], v190, s[12:13]
	global_load_dwordx4 v[52:55], v190, s[12:13] offset:16
	global_load_dwordx4 v[56:59], v188, s[12:13]
	global_load_dwordx4 v[60:63], v188, s[12:13] offset:16
	s_add_i32 s15, s14, 0
	s_and_b32 s16, s15, 7
	s_lshr_b32 s17, s15, 3
	s_mul_i32 s28, s15, 0x6000
	s_add_u32 s18, s4, s28
	s_addc_u32 s19, s5, 0
	s_sub_u32 s20, s18, 0x6000
	s_subb_u32 s21, s19, 0
	s_sub_u32 s22, s18, 0xc000
	s_subb_u32 s23, s19, 0
	global_load_dwordx4 v[64:67], v186, s[22:23]
	global_load_dwordx4 v[68:71], v186, s[22:23] offset:256
	global_load_dwordx4 v[72:75], v186, s[20:21]
	global_load_dwordx4 v[76:79], v186, s[20:21] offset:256
	global_load_dwordx4 v[80:83], v186, s[18:19]
	global_load_dwordx4 v[84:87], v186, s[18:19] offset:256
	s_mov_b32 s29, 6
	s_cmp_gt_u32 s16, 1
	s_cbranch_scc1 .Lffn_p0_pfdone
	s_lshl_b32 s28, s17, 1
	s_add_i32 s28, s28, s16
	s_mul_i32 s28, s28, 0xc000
	s_add_u32 s24, s8, s28
	s_addc_u32 s25, s9, 0
	global_load_dwordx4 v[112:115], v190, s[24:25]
	global_load_dwordx4 v[116:119], v190, s[24:25] offset:16
	global_load_dwordx4 v[120:123], v188, s[24:25]
	global_load_dwordx4 v[124:127], v188, s[24:25] offset:16
	s_mov_b32 s29, 10
	s_cmp_eq_u32 s16, 0
	s_cbranch_scc0 .Lffn_p0_pfdone
	s_add_u32 s24, s24, 0xc000
	s_addc_u32 s25, s25, 0
	global_load_dwordx4 v[128:131], v190, s[24:25]
	global_load_dwordx4 v[132:135], v190, s[24:25] offset:16
	global_load_dwordx4 v[136:139], v188, s[24:25]
	global_load_dwordx4 v[140:143], v188, s[24:25] offset:16
	s_mov_b32 s29, 14
.Lffn_p0_pfdone:
	s_add_i32 s15, s14, 170
	s_and_b32 s16, s15, 7
	s_lshr_b32 s17, s15, 3
	s_mul_i32 s28, s15, 0x6000
	s_add_u32 s18, s4, s28
	s_addc_u32 s19, s5, 0
	s_sub_u32 s20, s18, 0x6000
	s_subb_u32 s21, s19, 0
	s_sub_u32 s22, s18, 0xc000
	s_subb_u32 s23, s19, 0
	global_load_dwordx4 v[88:91], v186, s[22:23]
	global_load_dwordx4 v[92:95], v186, s[22:23] offset:256
	global_load_dwordx4 v[96:99], v186, s[20:21]
	global_load_dwordx4 v[100:103], v186, s[20:21] offset:256
	global_load_dwordx4 v[104:107], v186, s[18:19]
	global_load_dwordx4 v[108:111], v186, s[18:19] offset:256
	s_mov_b32 s29, 6
	s_cmp_gt_u32 s16, 1
	s_cbranch_scc1 .Lffn_r0_pfdone
	s_lshl_b32 s28, s17, 1
	s_add_i32 s28, s28, s16
	s_mul_i32 s28, s28, 0xc000
	s_add_u32 s24, s8, s28
	s_addc_u32 s25, s9, 0
	global_load_dwordx4 v[112:115], v190, s[24:25]
	global_load_dwordx4 v[116:119], v190, s[24:25] offset:16
	global_load_dwordx4 v[120:123], v188, s[24:25]
	global_load_dwordx4 v[124:127], v188, s[24:25] offset:16
	s_mov_b32 s29, 10
	s_cmp_eq_u32 s16, 0
	s_cbranch_scc0 .Lffn_r0_pfdone
	s_add_u32 s24, s24, 0xc000
	s_addc_u32 s25, s25, 0
	global_load_dwordx4 v[128:131], v190, s[24:25]
	global_load_dwordx4 v[132:135], v190, s[24:25] offset:16
	global_load_dwordx4 v[136:139], v188, s[24:25]
	global_load_dwordx4 v[140:143], v188, s[24:25] offset:16
	s_mov_b32 s29, 14
.Lffn_r0_pfdone:
	s_cmp_eq_u32 s29, 0
	s_cbranch_scc1 .Lffn_r0_w0
	s_cmp_eq_u32 s29, 6
	s_cbranch_scc1 .Lffn_r0_w6
	s_cmp_eq_u32 s29, 10
	s_cbranch_scc1 .Lffn_r0_w10
	s_waitcnt vmcnt(14)
	s_branch .Lffn_r0_wd
.Lffn_r0_w0:
	s_waitcnt vmcnt(0)
	s_branch .Lffn_r0_wd
.Lffn_r0_w6:
	s_waitcnt vmcnt(6)
	s_branch .Lffn_r0_wd
.Lffn_r0_w10:
	s_waitcnt vmcnt(10)
.Lffn_r0_wd:
	s_add_i32 s35, s14, 0
	s_and_b32 s30, s35, 7
	s_mul_i32 s28, s35, 0x3000
	s_add_u32 s26, s6, s28
	s_addc_u32 s27, s7, 0
	s_cmp_gt_u32 s30, 1
	s_cbranch_scc1 .Lffn_r0_t0up
	v_mov_b32_e32 v160, v112
	v_mov_b32_e32 v168, v120
	v_mov_b32_e32 v161, v113
	v_mov_b32_e32 v169, v121
	v_mov_b32_e32 v162, v114
	v_mov_b32_e32 v170, v122
	v_mov_b32_e32 v163, v115
	v_mov_b32_e32 v171, v123
	v_mov_b32_e32 v164, v116
	v_mov_b32_e32 v172, v124
	v_mov_b32_e32 v165, v117
	v_mov_b32_e32 v173, v125
	v_mov_b32_e32 v166, v118
	v_mov_b32_e32 v174, v126
	v_mov_b32_e32 v167, v119
	v_mov_b32_e32 v175, v127
	s_branch .Lffn_r0_t0d
; __device__ __forceinline__ float gelu_tanh(float x) { const float y = 1.5957691216f * (x + 0.044715f * x * x * x); return x * __builtin_amdgcn_rcpf(1.0f + __expf(-y)); }
; __device__ __forceinline__ void phase_ffnconv(const Params& p) {
;     ...
;             float xg[3][8], xv[3][8];
; #pragma unroll
;             for (int k = 0; k < 3; ++k) { const int tt = t - 2 + k;
;                 if (tt >= 0) { unpack8(*(const u32x4*)(UP + (size_t)(row - 2 + k) * 2 * DFF + colg), xg[k]); unpack8(*(const u32x4*)(UP + (size_t)(row - 2 + k) * 2 * DFF + colg + 128), xv[k]); }
;                 else { const float* sp = p.in[I_SFCONV] + ((size_t)b * 2 + (2 + tt)) * 2 * DFF; ld8f(sp + j0, xg[k]); ld8f(sp + DFF + j0, xv[k]); } }
;             float f[8];
; #pragma unroll
;             for (int e = 0; e < 8; ++e) { const float cg_ = bg[e] + xg[0][e] * wg[0][e] + xg[1][e] * wg[1][e] + xg[2][e] * wg[2][e];
;                 const float cv_ = bv[e] + xv[0][e] * wv[0][e] + xv[1][e] * wv[1][e] + xv[2][e] * wv[2][e]; f[e] = gelu_tanh(cg_) * cv_; }
.Lffn_r0_t0up:
	v_lshlrev_b32_e32 v160, 16, v64
	v_and_b32_e32 v161, 0xffff0000, v64
	v_lshlrev_b32_e32 v168, 16, v68
	v_and_b32_e32 v169, 0xffff0000, v68
	v_lshlrev_b32_e32 v162, 16, v65
	v_and_b32_e32 v163, 0xffff0000, v65
	v_lshlrev_b32_e32 v170, 16, v69
	v_and_b32_e32 v171, 0xffff0000, v69
	v_lshlrev_b32_e32 v164, 16, v66
	v_and_b32_e32 v165, 0xffff0000, v66
	v_lshlrev_b32_e32 v172, 16, v70
	v_and_b32_e32 v173, 0xffff0000, v70
	v_lshlrev_b32_e32 v166, 16, v67
	v_and_b32_e32 v167, 0xffff0000, v67
	v_lshlrev_b32_e32 v174, 16, v71
	v_and_b32_e32 v175, 0xffff0000, v71
.Lffn_r0_t0d:
	v_fma_f32 v144, v160, v0, v48
	v_fma_f32 v152, v168, v8, v56
	v_fma_f32 v145, v161, v1, v49
	v_fma_f32 v153, v169, v9, v57
	v_fma_f32 v146, v162, v2, v50
	v_fma_f32 v154, v170, v10, v58
	v_fma_f32 v147, v163, v3, v51
	v_fma_f32 v155, v171, v11, v59
	v_fma_f32 v148, v164, v4, v52
	v_fma_f32 v156, v172, v12, v60
	v_fma_f32 v149, v165, v5, v53
	v_fma_f32 v157, v173, v13, v61
	v_fma_f32 v150, v166, v6, v54
	v_fma_f32 v158, v174, v14, v62
	v_fma_f32 v151, v167, v7, v55
	v_fma_f32 v159, v175, v15, v63
	s_cmp_gt_u32 s30, 0
	s_cbranch_scc1 .Lffn_r0_t1up
	v_mov_b32_e32 v160, v128
	v_mov_b32_e32 v168, v136
	v_mov_b32_e32 v161, v129
	v_mov_b32_e32 v169, v137
	v_mov_b32_e32 v162, v130
	v_mov_b32_e32 v170, v138
	v_mov_b32_e32 v163, v131
	v_mov_b32_e32 v171, v139
	v_mov_b32_e32 v164, v132
	v_mov_b32_e32 v172, v140
	v_mov_b32_e32 v165, v133
	v_mov_b32_e32 v173, v141
	v_mov_b32_e32 v166, v134
	v_mov_b32_e32 v174, v142
	v_mov_b32_e32 v167, v135
	v_mov_b32_e32 v175, v143
	s_branch .Lffn_r0_t1d
.Lffn_r0_t1up:
	v_lshlrev_b32_e32 v160, 16, v72
	v_and_b32_e32 v161, 0xffff0000, v72
	v_lshlrev_b32_e32 v168, 16, v76
	v_and_b32_e32 v169, 0xffff0000, v76
	v_lshlrev_b32_e32 v162, 16, v73
	v_and_b32_e32 v163, 0xffff0000, v73
	v_lshlrev_b32_e32 v170, 16, v77
	v_and_b32_e32 v171, 0xffff0000, v77
	v_lshlrev_b32_e32 v164, 16, v74
	v_and_b32_e32 v165, 0xffff0000, v74
	v_lshlrev_b32_e32 v172, 16, v78
	v_and_b32_e32 v173, 0xffff0000, v78
	v_lshlrev_b32_e32 v166, 16, v75
	v_and_b32_e32 v167, 0xffff0000, v75
	v_lshlrev_b32_e32 v174, 16, v79
	v_and_b32_e32 v175, 0xffff0000, v79
.Lffn_r0_t1d:
	v_fmac_f32_e32 v144, v160, v16
	v_fmac_f32_e32 v152, v168, v24
	v_fmac_f32_e32 v145, v161, v17
	v_fmac_f32_e32 v153, v169, v25
	v_fmac_f32_e32 v146, v162, v18
	v_fmac_f32_e32 v154, v170, v26
	v_fmac_f32_e32 v147, v163, v19
	v_fmac_f32_e32 v155, v171, v27
	v_fmac_f32_e32 v148, v164, v20
	v_fmac_f32_e32 v156, v172, v28
	v_fmac_f32_e32 v149, v165, v21
	v_fmac_f32_e32 v157, v173, v29
	v_fmac_f32_e32 v150, v166, v22
	v_fmac_f32_e32 v158, v174, v30
	v_fmac_f32_e32 v151, v167, v23
	v_fmac_f32_e32 v159, v175, v31
	v_lshlrev_b32_e32 v160, 16, v80
	v_and_b32_e32 v161, 0xffff0000, v80
	v_lshlrev_b32_e32 v168, 16, v84
	v_and_b32_e32 v169, 0xffff0000, v84
	v_lshlrev_b32_e32 v162, 16, v81
	v_and_b32_e32 v163, 0xffff0000, v81
	v_lshlrev_b32_e32 v170, 16, v85
	v_and_b32_e32 v171, 0xffff0000, v85
	v_lshlrev_b32_e32 v164, 16, v82
	v_and_b32_e32 v165, 0xffff0000, v82
	v_lshlrev_b32_e32 v172, 16, v86
	v_and_b32_e32 v173, 0xffff0000, v86
	v_lshlrev_b32_e32 v166, 16, v83
	v_and_b32_e32 v167, 0xffff0000, v83
	v_lshlrev_b32_e32 v174, 16, v87
	v_and_b32_e32 v175, 0xffff0000, v87
	v_fmac_f32_e32 v144, v160, v32
	v_fmac_f32_e32 v152, v168, v40
	v_fmac_f32_e32 v145, v161, v33
	v_fmac_f32_e32 v153, v169, v41
	v_fmac_f32_e32 v146, v162, v34
	v_fmac_f32_e32 v154, v170, v42
	v_fmac_f32_e32 v147, v163, v35
	v_fmac_f32_e32 v155, v171, v43
	v_fmac_f32_e32 v148, v164, v36
	v_fmac_f32_e32 v156, v172, v44
	v_fmac_f32_e32 v149, v165, v37
	v_fmac_f32_e32 v157, v173, v45
	v_fmac_f32_e32 v150, v166, v38
	v_fmac_f32_e32 v158, v174, v46
	v_fmac_f32_e32 v151, v167, v39
	v_fmac_f32_e32 v159, v175, v47
	v_mul_f32_e32 v176, 0x3d372713, v144
	v_mul_f32_e32 v177, 0x3d372713, v145
	v_mul_f32_e32 v178, 0x3d372713, v146
	v_mul_f32_e32 v179, 0x3d372713, v147
	v_mul_f32_e32 v176, v144, v176
	v_mul_f32_e32 v177, v145, v177
	v_mul_f32_e32 v178, v146, v178
	v_mul_f32_e32 v179, v147, v179
	v_fma_f32 v176, v144, v176, v144
	v_fma_f32 v177, v145, v177, v145
	v_fma_f32 v178, v146, v178, v146
	v_fma_f32 v179, v147, v179, v147
	v_mul_f32_e32 v176, 0xbfcc422a, v176
	v_mul_f32_e32 v177, 0xbfcc422a, v177
	v_mul_f32_e32 v178, 0xbfcc422a, v178
	v_mul_f32_e32 v179, 0xbfcc422a, v179
	v_mul_f32_e32 v176, 0x3fb8aa3b, v176
	v_mul_f32_e32 v177, 0x3fb8aa3b, v177
	v_mul_f32_e32 v178, 0x3fb8aa3b, v178
	v_mul_f32_e32 v179, 0x3fb8aa3b, v179
	v_exp_f32_e32 v176, v176
	v_exp_f32_e32 v177, v177
	v_exp_f32_e32 v178, v178
	v_exp_f32_e32 v179, v179
	v_add_f32_e32 v176, 1.0, v176
	v_add_f32_e32 v177, 1.0, v177
	v_add_f32_e32 v178, 1.0, v178
	v_add_f32_e32 v179, 1.0, v179
	v_rcp_f32_e32 v176, v176
; __device__ __forceinline__ u32x4 pack8(const float (&f)[8]) { u32x4 w; w.x = pk2(f[0], f[1]); w.y = pk2(f[2], f[3]); w.z = pk2(f[4], f[5]); w.w = pk2(f[6], f[7]); return w; }
; __device__ __forceinline__ float gelu_tanh(float x) { const float y = 1.5957691216f * (x + 0.044715f * x * x * x); return x * __builtin_amdgcn_rcpf(1.0f + __expf(-y)); }
; __device__ __forceinline__ void phase_ffnconv(const Params& p) {
;     ...
;             for (int k = 0; k < 3; ++k) { const int tt = t - 2 + k;
;                 if (tt >= 0) { unpack8(*(const u32x4*)(UP + (size_t)(row - 2 + k) * 2 * DFF + colg), xg[k]); unpack8(*(const u32x4*)(UP + (size_t)(row - 2 + k) * 2 * DFF + colg + 128), xv[k]); }
;                 else { const float* sp = p.in[I_SFCONV] + ((size_t)b * 2 + (2 + tt)) * 2 * DFF; ld8f(sp + j0, xg[k]); ld8f(sp + DFF + j0, xv[k]); } }
;             float f[8];
; #pragma unroll
;             for (int e = 0; e < 8; ++e) { const float cg_ = bg[e] + xg[0][e] * wg[0][e] + xg[1][e] * wg[1][e] + xg[2][e] * wg[2][e];
;                 const float cv_ = bv[e] + xv[0][e] * wv[0][e] + xv[1][e] * wv[1][e] + xv[2][e] * wv[2][e]; f[e] = gelu_tanh(cg_) * cv_; }
;             *(u32x4*)(F + (size_t)row * DFF + j0) = pack8(f);
	v_rcp_f32_e32 v177, v177
	v_rcp_f32_e32 v178, v178
	v_rcp_f32_e32 v179, v179
	v_mul_f32_e32 v176, v144, v176
	v_mul_f32_e32 v177, v145, v177
	v_mul_f32_e32 v178, v146, v178
	v_mul_f32_e32 v179, v147, v179
	v_mul_f32_e32 v144, v176, v152
	v_mul_f32_e32 v145, v177, v153
	v_mul_f32_e32 v146, v178, v154
	v_mul_f32_e32 v147, v179, v155
	v_mul_f32_e32 v176, 0x3d372713, v148
	v_mul_f32_e32 v177, 0x3d372713, v149
	v_mul_f32_e32 v178, 0x3d372713, v150
	v_mul_f32_e32 v179, 0x3d372713, v151
	v_mul_f32_e32 v176, v148, v176
	v_mul_f32_e32 v177, v149, v177
	v_mul_f32_e32 v178, v150, v178
	v_mul_f32_e32 v179, v151, v179
	v_fma_f32 v176, v148, v176, v148
	v_fma_f32 v177, v149, v177, v149
	v_fma_f32 v178, v150, v178, v150
	v_fma_f32 v179, v151, v179, v151
	v_mul_f32_e32 v176, 0xbfcc422a, v176
	v_mul_f32_e32 v177, 0xbfcc422a, v177
	v_mul_f32_e32 v178, 0xbfcc422a, v178
	v_mul_f32_e32 v179, 0xbfcc422a, v179
	v_mul_f32_e32 v176, 0x3fb8aa3b, v176
	v_mul_f32_e32 v177, 0x3fb8aa3b, v177
	v_mul_f32_e32 v178, 0x3fb8aa3b, v178
	v_mul_f32_e32 v179, 0x3fb8aa3b, v179
	v_exp_f32_e32 v176, v176
	v_exp_f32_e32 v177, v177
	v_exp_f32_e32 v178, v178
	v_exp_f32_e32 v179, v179
	v_add_f32_e32 v176, 1.0, v176
	v_add_f32_e32 v177, 1.0, v177
	v_add_f32_e32 v178, 1.0, v178
	v_add_f32_e32 v179, 1.0, v179
	v_rcp_f32_e32 v176, v176
	v_rcp_f32_e32 v177, v177
	v_rcp_f32_e32 v178, v178
	v_rcp_f32_e32 v179, v179
	v_mul_f32_e32 v176, v148, v176
	v_mul_f32_e32 v177, v149, v177
	v_mul_f32_e32 v178, v150, v178
	v_mul_f32_e32 v179, v151, v179
	v_mul_f32_e32 v148, v176, v156
	v_mul_f32_e32 v149, v177, v157
	v_mul_f32_e32 v150, v178, v158
	v_mul_f32_e32 v151, v179, v159
	v_cvt_pk_bf16_f32 v180, v144, v145
	v_cvt_pk_bf16_f32 v181, v146, v147
	v_cvt_pk_bf16_f32 v182, v148, v149
	v_cvt_pk_bf16_f32 v183, v150, v151
	global_store_dwordx4 v189, v[180:183], s[26:27]
	s_add_i32 s15, s14, 340
	s_and_b32 s16, s15, 7
	s_lshr_b32 s17, s15, 3
	s_mul_i32 s28, s15, 0x6000
	s_add_u32 s18, s4, s28
	s_addc_u32 s19, s5, 0
	s_sub_u32 s20, s18, 0x6000
	s_subb_u32 s21, s19, 0
	s_sub_u32 s22, s18, 0xc000
	s_subb_u32 s23, s19, 0
	global_load_dwordx4 v[64:67], v186, s[22:23]
	global_load_dwordx4 v[68:71], v186, s[22:23] offset:256
	global_load_dwordx4 v[72:75], v186, s[20:21]
	global_load_dwordx4 v[76:79], v186, s[20:21] offset:256
	global_load_dwordx4 v[80:83], v186, s[18:19]
	global_load_dwordx4 v[84:87], v186, s[18:19] offset:256
	s_mov_b32 s29, 6
	s_cmp_gt_u32 s16, 1
	s_cbranch_scc1 .Lffn_r1_pfdone
	s_lshl_b32 s28, s17, 1
	s_add_i32 s28, s28, s16
	s_mul_i32 s28, s28, 0xc000
	s_add_u32 s24, s8, s28
	s_addc_u32 s25, s9, 0
	global_load_dwordx4 v[112:115], v190, s[24:25]
	global_load_dwordx4 v[116:119], v190, s[24:25] offset:16
	global_load_dwordx4 v[120:123], v188, s[24:25]
	global_load_dwordx4 v[124:127], v188, s[24:25] offset:16
	s_mov_b32 s29, 10
	s_cmp_eq_u32 s16, 0
	s_cbranch_scc0 .Lffn_r1_pfdone
	s_add_u32 s24, s24, 0xc000
	s_addc_u32 s25, s25, 0
	global_load_dwordx4 v[128:131], v190, s[24:25]
	global_load_dwordx4 v[132:135], v190, s[24:25] offset:16
	global_load_dwordx4 v[136:139], v188, s[24:25]
	global_load_dwordx4 v[140:143], v188, s[24:25] offset:16
	s_mov_b32 s29, 14
.Lffn_r1_pfdone:
	s_cmp_eq_u32 s29, 0
	s_cbranch_scc1 .Lffn_r1_w0
	s_cmp_eq_u32 s29, 6
	s_cbranch_scc1 .Lffn_r1_w6
	s_cmp_eq_u32 s29, 10
	s_cbranch_scc1 .Lffn_r1_w10
	s_waitcnt vmcnt(15)
	s_branch .Lffn_r1_wd
.Lffn_r1_w0:
	s_waitcnt vmcnt(1)
	s_branch .Lffn_r1_wd
.Lffn_r1_w6:
	s_waitcnt vmcnt(7)
	s_branch .Lffn_r1_wd
.Lffn_r1_w10:
	s_waitcnt vmcnt(11)
.Lffn_r1_wd:
	s_add_i32 s35, s14, 170
	s_and_b32 s30, s35, 7
	s_mul_i32 s28, s35, 0x3000
	s_add_u32 s26, s6, s28
	s_addc_u32 s27, s7, 0
	s_cmp_gt_u32 s30, 1
	s_cbranch_scc1 .Lffn_r1_t0up
	v_mov_b32_e32 v160, v112
	v_mov_b32_e32 v168, v120
	v_mov_b32_e32 v161, v113
	v_mov_b32_e32 v169, v121
	v_mov_b32_e32 v162, v114
	v_mov_b32_e32 v170, v122
	v_mov_b32_e32 v163, v115
	v_mov_b32_e32 v171, v123
	v_mov_b32_e32 v164, v116
	v_mov_b32_e32 v172, v124
	v_mov_b32_e32 v165, v117
	v_mov_b32_e32 v173, v125
	v_mov_b32_e32 v166, v118
	v_mov_b32_e32 v174, v126
	v_mov_b32_e32 v167, v119
	v_mov_b32_e32 v175, v127
	s_branch .Lffn_r1_t0d
.Lffn_r1_t0up:
	v_lshlrev_b32_e32 v160, 16, v88
	v_and_b32_e32 v161, 0xffff0000, v88
	v_lshlrev_b32_e32 v168, 16, v92
	v_and_b32_e32 v169, 0xffff0000, v92
	v_lshlrev_b32_e32 v162, 16, v89
	v_and_b32_e32 v163, 0xffff0000, v89
	v_lshlrev_b32_e32 v170, 16, v93
	v_and_b32_e32 v171, 0xffff0000, v93
	v_lshlrev_b32_e32 v164, 16, v90
	v_and_b32_e32 v165, 0xffff0000, v90
	v_lshlrev_b32_e32 v172, 16, v94
	v_and_b32_e32 v173, 0xffff0000, v94
	v_lshlrev_b32_e32 v166, 16, v91
	v_and_b32_e32 v167, 0xffff0000, v91
	v_lshlrev_b32_e32 v174, 16, v95
	v_and_b32_e32 v175, 0xffff0000, v95

; __device__ __forceinline__ u32x4 pack8(const float (&f)[8]) { u32x4 w; w.x = pk2(f[0], f[1]); w.y = pk2(f[2], f[3]); w.z = pk2(f[4], f[5]); w.w = pk2(f[6], f[7]); return w; }
; __device__ __forceinline__ float gelu_tanh(float x) { const float y = 1.5957691216f * (x + 0.044715f * x * x * x); return x * __builtin_amdgcn_rcpf(1.0f + __expf(-y)); }
; __device__ __forceinline__ void phase_ffnconv(const Params& p) {
;     ...
;             for (int k = 0; k < 3; ++k) { const int tt = t - 2 + k;
;                 if (tt >= 0) { unpack8(*(const u32x4*)(UP + (size_t)(row - 2 + k) * 2 * DFF + colg), xg[k]); unpack8(*(const u32x4*)(UP + (size_t)(row - 2 + k) * 2 * DFF + colg + 128), xv[k]); }
;                 else { const float* sp = p.in[I_SFCONV] + ((size_t)b * 2 + (2 + tt)) * 2 * DFF; ld8f(sp + j0, xg[k]); ld8f(sp + DFF + j0, xv[k]); } }
;             float f[8];
; #pragma unroll
;             for (int e = 0; e < 8; ++e) { const float cg_ = bg[e] + xg[0][e] * wg[0][e] + xg[1][e] * wg[1][e] + xg[2][e] * wg[2][e];
;                 const float cv_ = bv[e] + xv[0][e] * wv[0][e] + xv[1][e] * wv[1][e] + xv[2][e] * wv[2][e]; f[e] = gelu_tanh(cg_) * cv_; }
;             *(u32x4*)(F + (size_t)row * DFF + j0) = pack8(f);
.Lffn_r1_t1up:
	v_lshlrev_b32_e32 v160, 16, v96
	v_and_b32_e32 v161, 0xffff0000, v96
	v_lshlrev_b32_e32 v168, 16, v100
	v_and_b32_e32 v169, 0xffff0000, v100
	v_lshlrev_b32_e32 v162, 16, v97
	v_and_b32_e32 v163, 0xffff0000, v97
	v_lshlrev_b32_e32 v170, 16, v101
	v_and_b32_e32 v171, 0xffff0000, v101
	v_lshlrev_b32_e32 v164, 16, v98
	v_and_b32_e32 v165, 0xffff0000, v98
	v_lshlrev_b32_e32 v172, 16, v102
	v_and_b32_e32 v173, 0xffff0000, v102
	v_lshlrev_b32_e32 v166, 16, v99
	v_and_b32_e32 v167, 0xffff0000, v99
	v_lshlrev_b32_e32 v174, 16, v103
	v_and_b32_e32 v175, 0xffff0000, v103
.Lffn_r1_t1d:
	v_fmac_f32_e32 v144, v160, v16
	v_fmac_f32_e32 v152, v168, v24
	v_fmac_f32_e32 v145, v161, v17
	v_fmac_f32_e32 v153, v169, v25
	v_fmac_f32_e32 v146, v162, v18
	v_fmac_f32_e32 v154, v170, v26
	v_fmac_f32_e32 v147, v163, v19
	v_fmac_f32_e32 v155, v171, v27
	v_fmac_f32_e32 v148, v164, v20
	v_fmac_f32_e32 v156, v172, v28
	v_fmac_f32_e32 v149, v165, v21
	v_fmac_f32_e32 v157, v173, v29
	v_fmac_f32_e32 v150, v166, v22
	v_fmac_f32_e32 v158, v174, v30
	v_fmac_f32_e32 v151, v167, v23
	v_fmac_f32_e32 v159, v175, v31
	v_lshlrev_b32_e32 v160, 16, v104
	v_and_b32_e32 v161, 0xffff0000, v104
	v_lshlrev_b32_e32 v168, 16, v108
	v_and_b32_e32 v169, 0xffff0000, v108
	v_lshlrev_b32_e32 v162, 16, v105
	v_and_b32_e32 v163, 0xffff0000, v105
	v_lshlrev_b32_e32 v170, 16, v109
	v_and_b32_e32 v171, 0xffff0000, v109
	v_lshlrev_b32_e32 v164, 16, v106
	v_and_b32_e32 v165, 0xffff0000, v106
	v_lshlrev_b32_e32 v172, 16, v110
	v_and_b32_e32 v173, 0xffff0000, v110
	v_lshlrev_b32_e32 v166, 16, v107
	v_and_b32_e32 v167, 0xffff0000, v107
	v_lshlrev_b32_e32 v174, 16, v111
	v_and_b32_e32 v175, 0xffff0000, v111
	v_fmac_f32_e32 v144, v160, v32
	v_fmac_f32_e32 v152, v168, v40
	v_fmac_f32_e32 v145, v161, v33
	v_fmac_f32_e32 v153, v169, v41
	v_fmac_f32_e32 v146, v162, v34
	v_fmac_f32_e32 v154, v170, v42
	v_fmac_f32_e32 v147, v163, v35
	v_fmac_f32_e32 v155, v171, v43
	v_fmac_f32_e32 v148, v164, v36
	v_fmac_f32_e32 v156, v172, v44
	v_fmac_f32_e32 v149, v165, v37
	v_fmac_f32_e32 v157, v173, v45
	v_fmac_f32_e32 v150, v166, v38
	v_fmac_f32_e32 v158, v174, v46
	v_fmac_f32_e32 v151, v167, v39
	v_fmac_f32_e32 v159, v175, v47
	v_mul_f32_e32 v176, 0x3d372713, v144
	v_mul_f32_e32 v177, 0x3d372713, v145
	v_mul_f32_e32 v178, 0x3d372713, v146
	v_mul_f32_e32 v179, 0x3d372713, v147
	v_mul_f32_e32 v176, v144, v176
	v_mul_f32_e32 v177, v145, v177
	v_mul_f32_e32 v178, v146, v178
	v_mul_f32_e32 v179, v147, v179
	v_fma_f32 v176, v144, v176, v144
	v_fma_f32 v177, v145, v177, v145
	v_fma_f32 v178, v146, v178, v146
	v_fma_f32 v179, v147, v179, v147
	v_mul_f32_e32 v176, 0xbfcc422a, v176
	v_mul_f32_e32 v177, 0xbfcc422a, v177
	v_mul_f32_e32 v178, 0xbfcc422a, v178
	v_mul_f32_e32 v179, 0xbfcc422a, v179
	v_mul_f32_e32 v176, 0x3fb8aa3b, v176
	v_mul_f32_e32 v177, 0x3fb8aa3b, v177
	v_mul_f32_e32 v178, 0x3fb8aa3b, v178
	v_mul_f32_e32 v179, 0x3fb8aa3b, v179
	v_exp_f32_e32 v176, v176
	v_exp_f32_e32 v177, v177
	v_exp_f32_e32 v178, v178
	v_exp_f32_e32 v179, v179
	v_add_f32_e32 v176, 1.0, v176
	v_add_f32_e32 v177, 1.0, v177
	v_add_f32_e32 v178, 1.0, v178
	v_add_f32_e32 v179, 1.0, v179
	v_rcp_f32_e32 v176, v176
	v_rcp_f32_e32 v177, v177
	v_rcp_f32_e32 v178, v178
	v_rcp_f32_e32 v179, v179
	v_mul_f32_e32 v176, v144, v176
	v_mul_f32_e32 v177, v145, v177
	v_mul_f32_e32 v178, v146, v178
	v_mul_f32_e32 v179, v147, v179
	v_mul_f32_e32 v144, v176, v152
	v_mul_f32_e32 v145, v177, v153
	v_mul_f32_e32 v146, v178, v154
	v_mul_f32_e32 v147, v179, v155
	v_mul_f32_e32 v176, 0x3d372713, v148
	v_mul_f32_e32 v177, 0x3d372713, v149
	v_mul_f32_e32 v178, 0x3d372713, v150
	v_mul_f32_e32 v179, 0x3d372713, v151
	v_mul_f32_e32 v176, v148, v176
	v_mul_f32_e32 v177, v149, v177
	v_mul_f32_e32 v178, v150, v178
	v_mul_f32_e32 v179, v151, v179
	v_fma_f32 v176, v148, v176, v148
	v_fma_f32 v177, v149, v177, v149
	v_fma_f32 v178, v150, v178, v150
	v_fma_f32 v179, v151, v179, v151
	v_mul_f32_e32 v176, 0xbfcc422a, v176
	v_mul_f32_e32 v177, 0xbfcc422a, v177
	v_mul_f32_e32 v178, 0xbfcc422a, v178
	v_mul_f32_e32 v179, 0xbfcc422a, v179
	v_mul_f32_e32 v176, 0x3fb8aa3b, v176
	v_mul_f32_e32 v177, 0x3fb8aa3b, v177
	v_mul_f32_e32 v178, 0x3fb8aa3b, v178
	v_mul_f32_e32 v179, 0x3fb8aa3b, v179
	v_exp_f32_e32 v176, v176
	v_exp_f32_e32 v177, v177
	v_exp_f32_e32 v178, v178
	v_exp_f32_e32 v179, v179
	v_add_f32_e32 v176, 1.0, v176
	v_add_f32_e32 v177, 1.0, v177
	v_add_f32_e32 v178, 1.0, v178
	v_add_f32_e32 v179, 1.0, v179
	v_rcp_f32_e32 v176, v176
	v_rcp_f32_e32 v177, v177
	v_rcp_f32_e32 v178, v178
	v_rcp_f32_e32 v179, v179
	v_mul_f32_e32 v176, v148, v176
	v_mul_f32_e32 v177, v149, v177
	v_mul_f32_e32 v178, v150, v178
	v_mul_f32_e32 v179, v151, v179
	v_mul_f32_e32 v148, v176, v156
	v_mul_f32_e32 v149, v177, v157
	v_mul_f32_e32 v150, v178, v158
	v_mul_f32_e32 v151, v179, v159
	v_cvt_pk_bf16_f32 v180, v144, v145
	v_cvt_pk_bf16_f32 v181, v146, v147
	v_cvt_pk_bf16_f32 v182, v148, v149
	v_cvt_pk_bf16_f32 v183, v150, v151
	global_store_dwordx4 v189, v[180:183], s[26:27]
	s_add_i32 s15, s14, 510
	s_and_b32 s16, s15, 7
	s_lshr_b32 s17, s15, 3
	s_mul_i32 s28, s15, 0x6000
	s_add_u32 s18, s4, s28
	s_addc_u32 s19, s5, 0
	s_sub_u32 s20, s18, 0x6000
	s_subb_u32 s21, s19, 0
	s_sub_u32 s22, s18, 0xc000
	s_subb_u32 s23, s19, 0
	global_load_dwordx4 v[88:91], v186, s[22:23]
	global_load_dwordx4 v[92:95], v186, s[22:23] offset:256
	global_load_dwordx4 v[96:99], v186, s[20:21]
	global_load_dwordx4 v[100:103], v186, s[20:21] offset:256
	global_load_dwordx4 v[104:107], v186, s[18:19]
	global_load_dwordx4 v[108:111], v186, s[18:19] offset:256
	s_mov_b32 s29, 6
	s_cmp_gt_u32 s16, 1
	s_cbranch_scc1 .Lffn_r2_pfdone
	s_lshl_b32 s28, s17, 1
	s_add_i32 s28, s28, s16
	s_mul_i32 s28, s28, 0xc000
	s_add_u32 s24, s8, s28
	s_addc_u32 s25, s9, 0
	global_load_dwordx4 v[112:115], v190, s[24:25]
	global_load_dwordx4 v[116:119], v190, s[24:25] offset:16
	global_load_dwordx4 v[120:123], v188, s[24:25]
	global_load_dwordx4 v[124:127], v188, s[24:25] offset:16
	s_mov_b32 s29, 10
	s_cmp_eq_u32 s16, 0
	s_cbranch_scc0 .Lffn_r2_pfdone
	s_add_u32 s24, s24, 0xc000
	s_addc_u32 s25, s25, 0
	global_load_dwordx4 v[128:131], v190, s[24:25]
	global_load_dwordx4 v[132:135], v190, s[24:25] offset:16
	global_load_dwordx4 v[136:139], v188, s[24:25]
	global_load_dwordx4 v[140:143], v188, s[24:25] offset:16
	s_mov_b32 s29, 14

; __device__ __forceinline__ void phase_ffnconv(const Params& p) {
;     ...
;             for (int k = 0; k < 3; ++k) { const int tt = t - 2 + k;
;                 if (tt >= 0) { unpack8(*(const u32x4*)(UP + (size_t)(row - 2 + k) * 2 * DFF + colg), xg[k]); unpack8(*(const u32x4*)(UP + (size_t)(row - 2 + k) * 2 * DFF + colg + 128), xv[k]); }
;                 else { const float* sp = p.in[I_SFCONV] + ((size_t)b * 2 + (2 + tt)) * 2 * DFF; ld8f(sp + j0, xg[k]); ld8f(sp + DFF + j0, xv[k]); } }
.Lffn_r2_wd:
	s_add_i32 s35, s14, 340
	s_and_b32 s30, s35, 7
	s_mul_i32 s28, s35, 0x3000
	s_add_u32 s26, s6, s28
	s_addc_u32 s27, s7, 0
	s_cmp_gt_u32 s30, 1
	s_cbranch_scc1 .Lffn_r2_t0up
	v_mov_b32_e32 v160, v112
	v_mov_b32_e32 v168, v120
	v_mov_b32_e32 v161, v113
	v_mov_b32_e32 v169, v121
	v_mov_b32_e32 v162, v114
	v_mov_b32_e32 v170, v122
	v_mov_b32_e32 v163, v115
	v_mov_b32_e32 v171, v123
	v_mov_b32_e32 v164, v116
	v_mov_b32_e32 v172, v124
	v_mov_b32_e32 v165, v117
	v_mov_b32_e32 v173, v125
	v_mov_b32_e32 v166, v118
	v_mov_b32_e32 v174, v126
	v_mov_b32_e32 v167, v119
	v_mov_b32_e32 v175, v127
	s_branch .Lffn_r2_t0d

; __device__ __forceinline__ u32x4 pack8(const float (&f)[8]) { u32x4 w; w.x = pk2(f[0], f[1]); w.y = pk2(f[2], f[3]); w.z = pk2(f[4], f[5]); w.w = pk2(f[6], f[7]); return w; }
; __device__ __forceinline__ float gelu_tanh(float x) { const float y = 1.5957691216f * (x + 0.044715f * x * x * x); return x * __builtin_amdgcn_rcpf(1.0f + __expf(-y)); }
; __device__ __forceinline__ void phase_ffnconv(const Params& p) {
;     ...
;             for (int k = 0; k < 3; ++k) { const int tt = t - 2 + k;
;                 if (tt >= 0) { unpack8(*(const u32x4*)(UP + (size_t)(row - 2 + k) * 2 * DFF + colg), xg[k]); unpack8(*(const u32x4*)(UP + (size_t)(row - 2 + k) * 2 * DFF + colg + 128), xv[k]); }
;                 else { const float* sp = p.in[I_SFCONV] + ((size_t)b * 2 + (2 + tt)) * 2 * DFF; ld8f(sp + j0, xg[k]); ld8f(sp + DFF + j0, xv[k]); } }
;             float f[8];
; #pragma unroll
;             for (int e = 0; e < 8; ++e) { const float cg_ = bg[e] + xg[0][e] * wg[0][e] + xg[1][e] * wg[1][e] + xg[2][e] * wg[2][e];
;                 const float cv_ = bv[e] + xv[0][e] * wv[0][e] + xv[1][e] * wv[1][e] + xv[2][e] * wv[2][e]; f[e] = gelu_tanh(cg_) * cv_; }
;             *(u32x4*)(F + (size_t)row * DFF + j0) = pack8(f);
.Lffn_r2_t1d:
	v_fmac_f32_e32 v144, v160, v16
	v_fmac_f32_e32 v152, v168, v24
	v_fmac_f32_e32 v145, v161, v17
	v_fmac_f32_e32 v153, v169, v25
	v_fmac_f32_e32 v146, v162, v18
	v_fmac_f32_e32 v154, v170, v26
	v_fmac_f32_e32 v147, v163, v19
	v_fmac_f32_e32 v155, v171, v27
	v_fmac_f32_e32 v148, v164, v20
	v_fmac_f32_e32 v156, v172, v28
	v_fmac_f32_e32 v149, v165, v21
	v_fmac_f32_e32 v157, v173, v29
	v_fmac_f32_e32 v150, v166, v22
	v_fmac_f32_e32 v158, v174, v30
	v_fmac_f32_e32 v151, v167, v23
	v_fmac_f32_e32 v159, v175, v31
	v_lshlrev_b32_e32 v160, 16, v80
	v_and_b32_e32 v161, 0xffff0000, v80
	v_lshlrev_b32_e32 v168, 16, v84
	v_and_b32_e32 v169, 0xffff0000, v84
	v_lshlrev_b32_e32 v162, 16, v81
	v_and_b32_e32 v163, 0xffff0000, v81
	v_lshlrev_b32_e32 v170, 16, v85
	v_and_b32_e32 v171, 0xffff0000, v85
	v_lshlrev_b32_e32 v164, 16, v82
	v_and_b32_e32 v165, 0xffff0000, v82
	v_lshlrev_b32_e32 v172, 16, v86
	v_and_b32_e32 v173, 0xffff0000, v86
	v_lshlrev_b32_e32 v166, 16, v83
	v_and_b32_e32 v167, 0xffff0000, v83
	v_lshlrev_b32_e32 v174, 16, v87
	v_and_b32_e32 v175, 0xffff0000, v87
	v_fmac_f32_e32 v144, v160, v32
	v_fmac_f32_e32 v152, v168, v40
	v_fmac_f32_e32 v145, v161, v33
	v_fmac_f32_e32 v153, v169, v41
	v_fmac_f32_e32 v146, v162, v34
	v_fmac_f32_e32 v154, v170, v42
	v_fmac_f32_e32 v147, v163, v35
	v_fmac_f32_e32 v155, v171, v43
	v_fmac_f32_e32 v148, v164, v36
	v_fmac_f32_e32 v156, v172, v44
	v_fmac_f32_e32 v149, v165, v37
	v_fmac_f32_e32 v157, v173, v45
	v_fmac_f32_e32 v150, v166, v38
	v_fmac_f32_e32 v158, v174, v46
	v_fmac_f32_e32 v151, v167, v39
	v_fmac_f32_e32 v159, v175, v47
	v_mul_f32_e32 v176, 0x3d372713, v144
	v_mul_f32_e32 v177, 0x3d372713, v145
	v_mul_f32_e32 v178, 0x3d372713, v146
	v_mul_f32_e32 v179, 0x3d372713, v147
	v_mul_f32_e32 v176, v144, v176
	v_mul_f32_e32 v177, v145, v177
	v_mul_f32_e32 v178, v146, v178
	v_mul_f32_e32 v179, v147, v179
	v_fma_f32 v176, v144, v176, v144
	v_fma_f32 v177, v145, v177, v145
	v_fma_f32 v178, v146, v178, v146
	v_fma_f32 v179, v147, v179, v147
	v_mul_f32_e32 v176, 0xbfcc422a, v176
	v_mul_f32_e32 v177, 0xbfcc422a, v177
	v_mul_f32_e32 v178, 0xbfcc422a, v178
	v_mul_f32_e32 v179, 0xbfcc422a, v179
	v_mul_f32_e32 v176, 0x3fb8aa3b, v176
	v_mul_f32_e32 v177, 0x3fb8aa3b, v177
	v_mul_f32_e32 v178, 0x3fb8aa3b, v178
	v_mul_f32_e32 v179, 0x3fb8aa3b, v179
	v_exp_f32_e32 v176, v176
	v_exp_f32_e32 v177, v177
	v_exp_f32_e32 v178, v178
	v_exp_f32_e32 v179, v179
	v_add_f32_e32 v176, 1.0, v176
	v_add_f32_e32 v177, 1.0, v177
	v_add_f32_e32 v178, 1.0, v178
	v_add_f32_e32 v179, 1.0, v179
	v_rcp_f32_e32 v176, v176
	v_rcp_f32_e32 v177, v177
	v_rcp_f32_e32 v178, v178
	v_rcp_f32_e32 v179, v179
	v_mul_f32_e32 v176, v144, v176
	v_mul_f32_e32 v177, v145, v177
	v_mul_f32_e32 v178, v146, v178
	v_mul_f32_e32 v179, v147, v179
	v_mul_f32_e32 v144, v176, v152
	v_mul_f32_e32 v145, v177, v153
	v_mul_f32_e32 v146, v178, v154
	v_mul_f32_e32 v147, v179, v155
	v_mul_f32_e32 v176, 0x3d372713, v148
	v_mul_f32_e32 v177, 0x3d372713, v149
	v_mul_f32_e32 v178, 0x3d372713, v150
	v_mul_f32_e32 v179, 0x3d372713, v151
	v_mul_f32_e32 v176, v148, v176
	v_mul_f32_e32 v177, v149, v177
	v_mul_f32_e32 v178, v150, v178
	v_mul_f32_e32 v179, v151, v179
	v_fma_f32 v176, v148, v176, v148
	v_fma_f32 v177, v149, v177, v149
	v_fma_f32 v178, v150, v178, v150
	v_fma_f32 v179, v151, v179, v151
	v_mul_f32_e32 v176, 0xbfcc422a, v176
	v_mul_f32_e32 v177, 0xbfcc422a, v177
	v_mul_f32_e32 v178, 0xbfcc422a, v178
	v_mul_f32_e32 v179, 0xbfcc422a, v179
	v_mul_f32_e32 v176, 0x3fb8aa3b, v176
	v_mul_f32_e32 v177, 0x3fb8aa3b, v177
	v_mul_f32_e32 v178, 0x3fb8aa3b, v178
	v_mul_f32_e32 v179, 0x3fb8aa3b, v179
	v_exp_f32_e32 v176, v176
	v_exp_f32_e32 v177, v177
	v_exp_f32_e32 v178, v178
	v_exp_f32_e32 v179, v179
	v_add_f32_e32 v176, 1.0, v176
	v_add_f32_e32 v177, 1.0, v177
	v_add_f32_e32 v178, 1.0, v178
	v_add_f32_e32 v179, 1.0, v179
	v_rcp_f32_e32 v176, v176
	v_rcp_f32_e32 v177, v177
	v_rcp_f32_e32 v178, v178
	v_rcp_f32_e32 v179, v179
	v_mul_f32_e32 v176, v148, v176
	v_mul_f32_e32 v177, v149, v177
	v_mul_f32_e32 v178, v150, v178
	v_mul_f32_e32 v179, v151, v179
	v_mul_f32_e32 v148, v176, v156
	v_mul_f32_e32 v149, v177, v157
	v_mul_f32_e32 v150, v178, v158
	v_mul_f32_e32 v151, v179, v159
	v_cvt_pk_bf16_f32 v180, v144, v145
	v_cvt_pk_bf16_f32 v181, v146, v147
	v_cvt_pk_bf16_f32 v182, v148, v149
	v_cvt_pk_bf16_f32 v183, v150, v151
	global_store_dwordx4 v189, v[180:183], s[26:27]
	s_add_i32 s15, s14, 680
	s_and_b32 s16, s15, 7
	s_lshr_b32 s17, s15, 3
	s_mul_i32 s28, s15, 0x6000
	s_add_u32 s18, s4, s28
	s_addc_u32 s19, s5, 0
	s_sub_u32 s20, s18, 0x6000
	s_subb_u32 s21, s19, 0
	s_sub_u32 s22, s18, 0xc000
	s_subb_u32 s23, s19, 0
	global_load_dwordx4 v[64:67], v186, s[22:23]
	global_load_dwordx4 v[68:71], v186, s[22:23] offset:256
	global_load_dwordx4 v[72:75], v186, s[20:21]
	global_load_dwordx4 v[76:79], v186, s[20:21] offset:256
	global_load_dwordx4 v[80:83], v186, s[18:19]
	global_load_dwordx4 v[84:87], v186, s[18:19] offset:256
	s_mov_b32 s29, 6
	s_cmp_gt_u32 s16, 1
	s_cbranch_scc1 .Lffn_r3_pfdone
	s_lshl_b32 s28, s17, 1
	s_add_i32 s28, s28, s16
	s_mul_i32 s28, s28, 0xc000
	s_add_u32 s24, s8, s28
	s_addc_u32 s25, s9, 0
	global_load_dwordx4 v[112:115], v190, s[24:25]
	global_load_dwordx4 v[116:119], v190, s[24:25] offset:16
	global_load_dwordx4 v[120:123], v188, s[24:25]
	global_load_dwordx4 v[124:127], v188, s[24:25] offset:16
	s_mov_b32 s29, 10
	s_cmp_eq_u32 s16, 0
	s_cbranch_scc0 .Lffn_r3_pfdone
	s_add_u32 s24, s24, 0xc000
	s_addc_u32 s25, s25, 0
	global_load_dwordx4 v[128:131], v190, s[24:25]
	global_load_dwordx4 v[132:135], v190, s[24:25] offset:16
	global_load_dwordx4 v[136:139], v188, s[24:25]
	global_load_dwordx4 v[140:143], v188, s[24:25] offset:16
	s_mov_b32 s29, 14

; __device__ __forceinline__ void phase_ffnconv(const Params& p) {
;     ...
;             for (int k = 0; k < 3; ++k) { const int tt = t - 2 + k;
;                 if (tt >= 0) { unpack8(*(const u32x4*)(UP + (size_t)(row - 2 + k) * 2 * DFF + colg), xg[k]); unpack8(*(const u32x4*)(UP + (size_t)(row - 2 + k) * 2 * DFF + colg + 128), xv[k]); }
;                 else { const float* sp = p.in[I_SFCONV] + ((size_t)b * 2 + (2 + tt)) * 2 * DFF; ld8f(sp + j0, xg[k]); ld8f(sp + DFF + j0, xv[k]); } }
.Lffn_r3_wd:
	s_add_i32 s35, s14, 510
	s_and_b32 s30, s35, 7
	s_mul_i32 s28, s35, 0x3000
	s_add_u32 s26, s6, s28
	s_addc_u32 s27, s7, 0
	s_cmp_gt_u32 s30, 1
	s_cbranch_scc1 .Lffn_r3_t0up
	v_mov_b32_e32 v160, v112
	v_mov_b32_e32 v168, v120
	v_mov_b32_e32 v161, v113
	v_mov_b32_e32 v169, v121
	v_mov_b32_e32 v162, v114
	v_mov_b32_e32 v170, v122
	v_mov_b32_e32 v163, v115
	v_mov_b32_e32 v171, v123
	v_mov_b32_e32 v164, v116
	v_mov_b32_e32 v172, v124
	v_mov_b32_e32 v165, v117
	v_mov_b32_e32 v173, v125
	v_mov_b32_e32 v166, v118
	v_mov_b32_e32 v174, v126
	v_mov_b32_e32 v167, v119
	v_mov_b32_e32 v175, v127
	s_branch .Lffn_r3_t0d

; __device__ __forceinline__ u32x4 pack8(const float (&f)[8]) { u32x4 w; w.x = pk2(f[0], f[1]); w.y = pk2(f[2], f[3]); w.z = pk2(f[4], f[5]); w.w = pk2(f[6], f[7]); return w; }
; __device__ __forceinline__ float gelu_tanh(float x) { const float y = 1.5957691216f * (x + 0.044715f * x * x * x); return x * __builtin_amdgcn_rcpf(1.0f + __expf(-y)); }
; __device__ __forceinline__ void phase_ffnconv(const Params& p) {
;     ...
;             for (int k = 0; k < 3; ++k) { const int tt = t - 2 + k;
;                 if (tt >= 0) { unpack8(*(const u32x4*)(UP + (size_t)(row - 2 + k) * 2 * DFF + colg), xg[k]); unpack8(*(const u32x4*)(UP + (size_t)(row - 2 + k) * 2 * DFF + colg + 128), xv[k]); }
;                 else { const float* sp = p.in[I_SFCONV] + ((size_t)b * 2 + (2 + tt)) * 2 * DFF; ld8f(sp + j0, xg[k]); ld8f(sp + DFF + j0, xv[k]); } }
;             float f[8];
; #pragma unroll
;             for (int e = 0; e < 8; ++e) { const float cg_ = bg[e] + xg[0][e] * wg[0][e] + xg[1][e] * wg[1][e] + xg[2][e] * wg[2][e];
;                 const float cv_ = bv[e] + xv[0][e] * wv[0][e] + xv[1][e] * wv[1][e] + xv[2][e] * wv[2][e]; f[e] = gelu_tanh(cg_) * cv_; }
;             *(u32x4*)(F + (size_t)row * DFF + j0) = pack8(f);
.Lffn_r3_t1d:
	v_fmac_f32_e32 v144, v160, v16
	v_fmac_f32_e32 v152, v168, v24
	v_fmac_f32_e32 v145, v161, v17
	v_fmac_f32_e32 v153, v169, v25
	v_fmac_f32_e32 v146, v162, v18
	v_fmac_f32_e32 v154, v170, v26
	v_fmac_f32_e32 v147, v163, v19
	v_fmac_f32_e32 v155, v171, v27
	v_fmac_f32_e32 v148, v164, v20
	v_fmac_f32_e32 v156, v172, v28
	v_fmac_f32_e32 v149, v165, v21
	v_fmac_f32_e32 v157, v173, v29
	v_fmac_f32_e32 v150, v166, v22
	v_fmac_f32_e32 v158, v174, v30
	v_fmac_f32_e32 v151, v167, v23
	v_fmac_f32_e32 v159, v175, v31
	v_lshlrev_b32_e32 v160, 16, v104
	v_and_b32_e32 v161, 0xffff0000, v104
	v_lshlrev_b32_e32 v168, 16, v108
	v_and_b32_e32 v169, 0xffff0000, v108
	v_lshlrev_b32_e32 v162, 16, v105
	v_and_b32_e32 v163, 0xffff0000, v105
	v_lshlrev_b32_e32 v170, 16, v109
	v_and_b32_e32 v171, 0xffff0000, v109
	v_lshlrev_b32_e32 v164, 16, v106
	v_and_b32_e32 v165, 0xffff0000, v106
	v_lshlrev_b32_e32 v172, 16, v110
	v_and_b32_e32 v173, 0xffff0000, v110
	v_lshlrev_b32_e32 v166, 16, v107
	v_and_b32_e32 v167, 0xffff0000, v107
	v_lshlrev_b32_e32 v174, 16, v111
	v_and_b32_e32 v175, 0xffff0000, v111
	v_fmac_f32_e32 v144, v160, v32
	v_fmac_f32_e32 v152, v168, v40
	v_fmac_f32_e32 v145, v161, v33
	v_fmac_f32_e32 v153, v169, v41
	v_fmac_f32_e32 v146, v162, v34
	v_fmac_f32_e32 v154, v170, v42
	v_fmac_f32_e32 v147, v163, v35
	v_fmac_f32_e32 v155, v171, v43
	v_fmac_f32_e32 v148, v164, v36
	v_fmac_f32_e32 v156, v172, v44
	v_fmac_f32_e32 v149, v165, v37
	v_fmac_f32_e32 v157, v173, v45
	v_fmac_f32_e32 v150, v166, v38
	v_fmac_f32_e32 v158, v174, v46
	v_fmac_f32_e32 v151, v167, v39
	v_fmac_f32_e32 v159, v175, v47
	v_mul_f32_e32 v176, 0x3d372713, v144
	v_mul_f32_e32 v177, 0x3d372713, v145
	v_mul_f32_e32 v178, 0x3d372713, v146
	v_mul_f32_e32 v179, 0x3d372713, v147
	v_mul_f32_e32 v176, v144, v176
	v_mul_f32_e32 v177, v145, v177
	v_mul_f32_e32 v178, v146, v178
	v_mul_f32_e32 v179, v147, v179
	v_fma_f32 v176, v144, v176, v144
	v_fma_f32 v177, v145, v177, v145
	v_fma_f32 v178, v146, v178, v146
	v_fma_f32 v179, v147, v179, v147
	v_mul_f32_e32 v176, 0xbfcc422a, v176
	v_mul_f32_e32 v177, 0xbfcc422a, v177
	v_mul_f32_e32 v178, 0xbfcc422a, v178
	v_mul_f32_e32 v179, 0xbfcc422a, v179
	v_mul_f32_e32 v176, 0x3fb8aa3b, v176
	v_mul_f32_e32 v177, 0x3fb8aa3b, v177
	v_mul_f32_e32 v178, 0x3fb8aa3b, v178
	v_mul_f32_e32 v179, 0x3fb8aa3b, v179
	v_exp_f32_e32 v176, v176
	v_exp_f32_e32 v177, v177
	v_exp_f32_e32 v178, v178
	v_exp_f32_e32 v179, v179
	v_add_f32_e32 v176, 1.0, v176
	v_add_f32_e32 v177, 1.0, v177
	v_add_f32_e32 v178, 1.0, v178
	v_add_f32_e32 v179, 1.0, v179
	v_rcp_f32_e32 v176, v176
	v_rcp_f32_e32 v177, v177
	v_rcp_f32_e32 v178, v178
	v_rcp_f32_e32 v179, v179
	v_mul_f32_e32 v176, v144, v176
	v_mul_f32_e32 v177, v145, v177
	v_mul_f32_e32 v178, v146, v178
	v_mul_f32_e32 v179, v147, v179
	v_mul_f32_e32 v144, v176, v152
	v_mul_f32_e32 v145, v177, v153
	v_mul_f32_e32 v146, v178, v154
	v_mul_f32_e32 v147, v179, v155
	v_mul_f32_e32 v176, 0x3d372713, v148
	v_mul_f32_e32 v177, 0x3d372713, v149
	v_mul_f32_e32 v178, 0x3d372713, v150
	v_mul_f32_e32 v179, 0x3d372713, v151
	v_mul_f32_e32 v176, v148, v176
	v_mul_f32_e32 v177, v149, v177
	v_mul_f32_e32 v178, v150, v178
	v_mul_f32_e32 v179, v151, v179
	v_fma_f32 v176, v148, v176, v148
	v_fma_f32 v177, v149, v177, v149
	v_fma_f32 v178, v150, v178, v150
	v_fma_f32 v179, v151, v179, v151
	v_mul_f32_e32 v176, 0xbfcc422a, v176
	v_mul_f32_e32 v177, 0xbfcc422a, v177
	v_mul_f32_e32 v178, 0xbfcc422a, v178
	v_mul_f32_e32 v179, 0xbfcc422a, v179
	v_mul_f32_e32 v176, 0x3fb8aa3b, v176
	v_mul_f32_e32 v177, 0x3fb8aa3b, v177
	v_mul_f32_e32 v178, 0x3fb8aa3b, v178
	v_mul_f32_e32 v179, 0x3fb8aa3b, v179
	v_exp_f32_e32 v176, v176
	v_exp_f32_e32 v177, v177
	v_exp_f32_e32 v178, v178
	v_exp_f32_e32 v179, v179
	v_add_f32_e32 v176, 1.0, v176
	v_add_f32_e32 v177, 1.0, v177
	v_add_f32_e32 v178, 1.0, v178
	v_add_f32_e32 v179, 1.0, v179
	v_rcp_f32_e32 v176, v176
	v_rcp_f32_e32 v177, v177
	v_rcp_f32_e32 v178, v178
	v_rcp_f32_e32 v179, v179
	v_mul_f32_e32 v176, v148, v176
	v_mul_f32_e32 v177, v149, v177
	v_mul_f32_e32 v178, v150, v178
	v_mul_f32_e32 v179, v151, v179
	v_mul_f32_e32 v148, v176, v156
	v_mul_f32_e32 v149, v177, v157
	v_mul_f32_e32 v150, v178, v158
	v_mul_f32_e32 v151, v179, v159
	v_cvt_pk_bf16_f32 v180, v144, v145
	v_cvt_pk_bf16_f32 v181, v146, v147
	v_cvt_pk_bf16_f32 v182, v148, v149
	v_cvt_pk_bf16_f32 v183, v150, v151
	global_store_dwordx4 v189, v[180:183], s[26:27]
	s_add_i32 s15, s14, 850
	s_and_b32 s16, s15, 7
	s_lshr_b32 s17, s15, 3
	s_mul_i32 s28, s15, 0x6000
	s_add_u32 s18, s4, s28
	s_addc_u32 s19, s5, 0
	s_sub_u32 s20, s18, 0x6000
	s_subb_u32 s21, s19, 0
	s_sub_u32 s22, s18, 0xc000
	s_subb_u32 s23, s19, 0
	global_load_dwordx4 v[88:91], v186, s[22:23]
	global_load_dwordx4 v[92:95], v186, s[22:23] offset:256
	global_load_dwordx4 v[96:99], v186, s[20:21]
	global_load_dwordx4 v[100:103], v186, s[20:21] offset:256
	global_load_dwordx4 v[104:107], v186, s[18:19]
	global_load_dwordx4 v[108:111], v186, s[18:19] offset:256
	s_mov_b32 s29, 6
	s_cmp_gt_u32 s16, 1
	s_cbranch_scc1 .Lffn_r4_pfdone
	s_lshl_b32 s28, s17, 1
	s_add_i32 s28, s28, s16
	s_mul_i32 s28, s28, 0xc000
	s_add_u32 s24, s8, s28
	s_addc_u32 s25, s9, 0
	global_load_dwordx4 v[112:115], v190, s[24:25]
	global_load_dwordx4 v[116:119], v190, s[24:25] offset:16
	global_load_dwordx4 v[120:123], v188, s[24:25]
	global_load_dwordx4 v[124:127], v188, s[24:25] offset:16
	s_mov_b32 s29, 10
	s_cmp_eq_u32 s16, 0
	s_cbranch_scc0 .Lffn_r4_pfdone
	s_add_u32 s24, s24, 0xc000
	s_addc_u32 s25, s25, 0
	global_load_dwordx4 v[128:131], v190, s[24:25]
	global_load_dwordx4 v[132:135], v190, s[24:25] offset:16
	global_load_dwordx4 v[136:139], v188, s[24:25]
	global_load_dwordx4 v[140:143], v188, s[24:25] offset:16
	s_mov_b32 s29, 14

; __device__ __forceinline__ void phase_ffnconv(const Params& p) {
;     ...
;             for (int k = 0; k < 3; ++k) { const int tt = t - 2 + k;
;                 if (tt >= 0) { unpack8(*(const u32x4*)(UP + (size_t)(row - 2 + k) * 2 * DFF + colg), xg[k]); unpack8(*(const u32x4*)(UP + (size_t)(row - 2 + k) * 2 * DFF + colg + 128), xv[k]); }
;                 else { const float* sp = p.in[I_SFCONV] + ((size_t)b * 2 + (2 + tt)) * 2 * DFF; ld8f(sp + j0, xg[k]); ld8f(sp + DFF + j0, xv[k]); } }
.Lffn_r4_wd:
	s_add_i32 s35, s14, 680
	s_and_b32 s30, s35, 7
	s_mul_i32 s28, s35, 0x3000
	s_add_u32 s26, s6, s28
	s_addc_u32 s27, s7, 0
	s_cmp_gt_u32 s30, 1
	s_cbranch_scc1 .Lffn_r4_t0up
	v_mov_b32_e32 v160, v112
	v_mov_b32_e32 v168, v120
	v_mov_b32_e32 v161, v113
	v_mov_b32_e32 v169, v121
	v_mov_b32_e32 v162, v114
	v_mov_b32_e32 v170, v122
	v_mov_b32_e32 v163, v115
	v_mov_b32_e32 v171, v123
	v_mov_b32_e32 v164, v116
	v_mov_b32_e32 v172, v124
	v_mov_b32_e32 v165, v117
	v_mov_b32_e32 v173, v125
	v_mov_b32_e32 v166, v118
	v_mov_b32_e32 v174, v126
	v_mov_b32_e32 v167, v119
	v_mov_b32_e32 v175, v127
	s_branch .Lffn_r4_t0d

; __device__ __forceinline__ u32x4 pack8(const float (&f)[8]) { u32x4 w; w.x = pk2(f[0], f[1]); w.y = pk2(f[2], f[3]); w.z = pk2(f[4], f[5]); w.w = pk2(f[6], f[7]); return w; }
; __device__ __forceinline__ float gelu_tanh(float x) { const float y = 1.5957691216f * (x + 0.044715f * x * x * x); return x * __builtin_amdgcn_rcpf(1.0f + __expf(-y)); }
; __device__ __forceinline__ void phase_ffnconv(const Params& p) {
;     ...
;             for (int k = 0; k < 3; ++k) { const int tt = t - 2 + k;
;                 if (tt >= 0) { unpack8(*(const u32x4*)(UP + (size_t)(row - 2 + k) * 2 * DFF + colg), xg[k]); unpack8(*(const u32x4*)(UP + (size_t)(row - 2 + k) * 2 * DFF + colg + 128), xv[k]); }
;                 else { const float* sp = p.in[I_SFCONV] + ((size_t)b * 2 + (2 + tt)) * 2 * DFF; ld8f(sp + j0, xg[k]); ld8f(sp + DFF + j0, xv[k]); } }
;             float f[8];
; #pragma unroll
;             for (int e = 0; e < 8; ++e) { const float cg_ = bg[e] + xg[0][e] * wg[0][e] + xg[1][e] * wg[1][e] + xg[2][e] * wg[2][e];
;                 const float cv_ = bv[e] + xv[0][e] * wv[0][e] + xv[1][e] * wv[1][e] + xv[2][e] * wv[2][e]; f[e] = gelu_tanh(cg_) * cv_; }
;             *(u32x4*)(F + (size_t)row * DFF + j0) = pack8(f);
.Lffn_r4_t1d:
	v_fmac_f32_e32 v144, v160, v16
	v_fmac_f32_e32 v152, v168, v24
	v_fmac_f32_e32 v145, v161, v17
	v_fmac_f32_e32 v153, v169, v25
	v_fmac_f32_e32 v146, v162, v18
	v_fmac_f32_e32 v154, v170, v26
	v_fmac_f32_e32 v147, v163, v19
	v_fmac_f32_e32 v155, v171, v27
	v_fmac_f32_e32 v148, v164, v20
	v_fmac_f32_e32 v156, v172, v28
	v_fmac_f32_e32 v149, v165, v21
	v_fmac_f32_e32 v157, v173, v29
	v_fmac_f32_e32 v150, v166, v22
	v_fmac_f32_e32 v158, v174, v30
	v_fmac_f32_e32 v151, v167, v23
	v_fmac_f32_e32 v159, v175, v31
	v_lshlrev_b32_e32 v160, 16, v80
	v_and_b32_e32 v161, 0xffff0000, v80
	v_lshlrev_b32_e32 v168, 16, v84
	v_and_b32_e32 v169, 0xffff0000, v84
	v_lshlrev_b32_e32 v162, 16, v81
	v_and_b32_e32 v163, 0xffff0000, v81
	v_lshlrev_b32_e32 v170, 16, v85
	v_and_b32_e32 v171, 0xffff0000, v85
	v_lshlrev_b32_e32 v164, 16, v82
	v_and_b32_e32 v165, 0xffff0000, v82
	v_lshlrev_b32_e32 v172, 16, v86
	v_and_b32_e32 v173, 0xffff0000, v86
	v_lshlrev_b32_e32 v166, 16, v83
	v_and_b32_e32 v167, 0xffff0000, v83
	v_lshlrev_b32_e32 v174, 16, v87
	v_and_b32_e32 v175, 0xffff0000, v87
	v_fmac_f32_e32 v144, v160, v32
	v_fmac_f32_e32 v152, v168, v40
	v_fmac_f32_e32 v145, v161, v33
	v_fmac_f32_e32 v153, v169, v41
	v_fmac_f32_e32 v146, v162, v34
	v_fmac_f32_e32 v154, v170, v42
	v_fmac_f32_e32 v147, v163, v35
	v_fmac_f32_e32 v155, v171, v43
	v_fmac_f32_e32 v148, v164, v36
	v_fmac_f32_e32 v156, v172, v44
	v_fmac_f32_e32 v149, v165, v37
	v_fmac_f32_e32 v157, v173, v45
	v_fmac_f32_e32 v150, v166, v38
	v_fmac_f32_e32 v158, v174, v46
	v_fmac_f32_e32 v151, v167, v39
	v_fmac_f32_e32 v159, v175, v47
	v_mul_f32_e32 v176, 0x3d372713, v144
	v_mul_f32_e32 v177, 0x3d372713, v145
	v_mul_f32_e32 v178, 0x3d372713, v146
	v_mul_f32_e32 v179, 0x3d372713, v147
	v_mul_f32_e32 v176, v144, v176
	v_mul_f32_e32 v177, v145, v177
	v_mul_f32_e32 v178, v146, v178
	v_mul_f32_e32 v179, v147, v179
	v_fma_f32 v176, v144, v176, v144
	v_fma_f32 v177, v145, v177, v145
	v_fma_f32 v178, v146, v178, v146
	v_fma_f32 v179, v147, v179, v147
	v_mul_f32_e32 v176, 0xbfcc422a, v176
	v_mul_f32_e32 v177, 0xbfcc422a, v177
	v_mul_f32_e32 v178, 0xbfcc422a, v178
	v_mul_f32_e32 v179, 0xbfcc422a, v179
	v_mul_f32_e32 v176, 0x3fb8aa3b, v176
	v_mul_f32_e32 v177, 0x3fb8aa3b, v177
	v_mul_f32_e32 v178, 0x3fb8aa3b, v178
	v_mul_f32_e32 v179, 0x3fb8aa3b, v179
	v_exp_f32_e32 v176, v176
	v_exp_f32_e32 v177, v177
	v_exp_f32_e32 v178, v178
	v_exp_f32_e32 v179, v179
	v_add_f32_e32 v176, 1.0, v176
	v_add_f32_e32 v177, 1.0, v177
	v_add_f32_e32 v178, 1.0, v178
	v_add_f32_e32 v179, 1.0, v179
	v_rcp_f32_e32 v176, v176
	v_rcp_f32_e32 v177, v177
	v_rcp_f32_e32 v178, v178
	v_rcp_f32_e32 v179, v179
	v_mul_f32_e32 v176, v144, v176
	v_mul_f32_e32 v177, v145, v177
	v_mul_f32_e32 v178, v146, v178
	v_mul_f32_e32 v179, v147, v179
	v_mul_f32_e32 v144, v176, v152
	v_mul_f32_e32 v145, v177, v153
	v_mul_f32_e32 v146, v178, v154
	v_mul_f32_e32 v147, v179, v155
	v_mul_f32_e32 v176, 0x3d372713, v148
	v_mul_f32_e32 v177, 0x3d372713, v149
	v_mul_f32_e32 v178, 0x3d372713, v150
	v_mul_f32_e32 v179, 0x3d372713, v151
	v_mul_f32_e32 v176, v148, v176
	v_mul_f32_e32 v177, v149, v177
	v_mul_f32_e32 v178, v150, v178
	v_mul_f32_e32 v179, v151, v179
	v_fma_f32 v176, v148, v176, v148
	v_fma_f32 v177, v149, v177, v149
	v_fma_f32 v178, v150, v178, v150
	v_fma_f32 v179, v151, v179, v151
	v_mul_f32_e32 v176, 0xbfcc422a, v176
	v_mul_f32_e32 v177, 0xbfcc422a, v177
	v_mul_f32_e32 v178, 0xbfcc422a, v178
	v_mul_f32_e32 v179, 0xbfcc422a, v179
	v_mul_f32_e32 v176, 0x3fb8aa3b, v176
	v_mul_f32_e32 v177, 0x3fb8aa3b, v177
	v_mul_f32_e32 v178, 0x3fb8aa3b, v178
	v_mul_f32_e32 v179, 0x3fb8aa3b, v179
	v_exp_f32_e32 v176, v176
	v_exp_f32_e32 v177, v177
	v_exp_f32_e32 v178, v178
	v_exp_f32_e32 v179, v179
	v_add_f32_e32 v176, 1.0, v176
	v_add_f32_e32 v177, 1.0, v177
	v_add_f32_e32 v178, 1.0, v178
	v_add_f32_e32 v179, 1.0, v179
	v_rcp_f32_e32 v176, v176
	v_rcp_f32_e32 v177, v177
	v_rcp_f32_e32 v178, v178
	v_rcp_f32_e32 v179, v179
	v_mul_f32_e32 v176, v148, v176
	v_mul_f32_e32 v177, v149, v177
	v_mul_f32_e32 v178, v150, v178
	v_mul_f32_e32 v179, v151, v179
	v_mul_f32_e32 v148, v176, v156
	v_mul_f32_e32 v149, v177, v157
	v_mul_f32_e32 v150, v178, v158
	v_mul_f32_e32 v151, v179, v159
	v_cvt_pk_bf16_f32 v180, v144, v145
	v_cvt_pk_bf16_f32 v181, v146, v147
	v_cvt_pk_bf16_f32 v182, v148, v149
	v_cvt_pk_bf16_f32 v183, v150, v151
	global_store_dwordx4 v189, v[180:183], s[26:27]
	s_add_i32 s15, s14, 1020
	s_mov_b32 s29, 0
	s_cmp_ge_u32 s15, 0x400
	s_cbranch_scc1 .Lffn_r5_pfdone
	s_and_b32 s16, s15, 7
	s_lshr_b32 s17, s15, 3
	s_mul_i32 s28, s15, 0x6000
	s_add_u32 s18, s4, s28
	s_addc_u32 s19, s5, 0
	s_sub_u32 s20, s18, 0x6000
	s_subb_u32 s21, s19, 0
	s_sub_u32 s22, s18, 0xc000
	s_subb_u32 s23, s19, 0
	global_load_dwordx4 v[64:67], v186, s[22:23]
	global_load_dwordx4 v[68:71], v186, s[22:23] offset:256
	global_load_dwordx4 v[72:75], v186, s[20:21]
	global_load_dwordx4 v[76:79], v186, s[20:21] offset:256
	global_load_dwordx4 v[80:83], v186, s[18:19]
	global_load_dwordx4 v[84:87], v186, s[18:19] offset:256
	s_mov_b32 s29, 6
	s_cmp_gt_u32 s16, 1
	s_cbranch_scc1 .Lffn_r5_pfdone
	s_lshl_b32 s28, s17, 1
	s_add_i32 s28, s28, s16
	s_mul_i32 s28, s28, 0xc000
	s_add_u32 s24, s8, s28
	s_addc_u32 s25, s9, 0
	global_load_dwordx4 v[112:115], v190, s[24:25]
	global_load_dwordx4 v[116:119], v190, s[24:25] offset:16
	global_load_dwordx4 v[120:123], v188, s[24:25]
	global_load_dwordx4 v[124:127], v188, s[24:25] offset:16
	s_mov_b32 s29, 10
	s_cmp_eq_u32 s16, 0
	s_cbranch_scc0 .Lffn_r5_pfdone
	s_add_u32 s24, s24, 0xc000
	s_addc_u32 s25, s25, 0
	global_load_dwordx4 v[128:131], v190, s[24:25]
	global_load_dwordx4 v[132:135], v190, s[24:25] offset:16
	global_load_dwordx4 v[136:139], v188, s[24:25]
	global_load_dwordx4 v[140:143], v188, s[24:25] offset:16
	s_mov_b32 s29, 14

; __device__ __forceinline__ void phase_ffnconv(const Params& p) {
;     ...
;             for (int k = 0; k < 3; ++k) { const int tt = t - 2 + k;
;                 if (tt >= 0) { unpack8(*(const u32x4*)(UP + (size_t)(row - 2 + k) * 2 * DFF + colg), xg[k]); unpack8(*(const u32x4*)(UP + (size_t)(row - 2 + k) * 2 * DFF + colg + 128), xv[k]); }
;                 else { const float* sp = p.in[I_SFCONV] + ((size_t)b * 2 + (2 + tt)) * 2 * DFF; ld8f(sp + j0, xg[k]); ld8f(sp + DFF + j0, xv[k]); } }
.Lffn_r5_wd:
	s_add_i32 s35, s14, 850
	s_and_b32 s30, s35, 7
	s_mul_i32 s28, s35, 0x3000
	s_add_u32 s26, s6, s28
	s_addc_u32 s27, s7, 0
	s_cmp_gt_u32 s30, 1
	s_cbranch_scc1 .Lffn_r5_t0up
	v_mov_b32_e32 v160, v112
	v_mov_b32_e32 v168, v120
	v_mov_b32_e32 v161, v113
	v_mov_b32_e32 v169, v121
	v_mov_b32_e32 v162, v114
	v_mov_b32_e32 v170, v122
	v_mov_b32_e32 v163, v115
	v_mov_b32_e32 v171, v123
	v_mov_b32_e32 v164, v116
	v_mov_b32_e32 v172, v124
	v_mov_b32_e32 v165, v117
	v_mov_b32_e32 v173, v125
	v_mov_b32_e32 v166, v118
	v_mov_b32_e32 v174, v126
	v_mov_b32_e32 v167, v119
	v_mov_b32_e32 v175, v127
	s_branch .Lffn_r5_t0d

; __device__ __forceinline__ u32x4 pack8(const float (&f)[8]) { u32x4 w; w.x = pk2(f[0], f[1]); w.y = pk2(f[2], f[3]); w.z = pk2(f[4], f[5]); w.w = pk2(f[6], f[7]); return w; }
; __device__ __forceinline__ float gelu_tanh(float x) { const float y = 1.5957691216f * (x + 0.044715f * x * x * x); return x * __builtin_amdgcn_rcpf(1.0f + __expf(-y)); }
; __device__ __forceinline__ void phase_ffnconv(const Params& p) {
;     ...
;             for (int k = 0; k < 3; ++k) { const int tt = t - 2 + k;
;                 if (tt >= 0) { unpack8(*(const u32x4*)(UP + (size_t)(row - 2 + k) * 2 * DFF + colg), xg[k]); unpack8(*(const u32x4*)(UP + (size_t)(row - 2 + k) * 2 * DFF + colg + 128), xv[k]); }
;                 else { const float* sp = p.in[I_SFCONV] + ((size_t)b * 2 + (2 + tt)) * 2 * DFF; ld8f(sp + j0, xg[k]); ld8f(sp + DFF + j0, xv[k]); } }
;             float f[8];
; #pragma unroll
;             for (int e = 0; e < 8; ++e) { const float cg_ = bg[e] + xg[0][e] * wg[0][e] + xg[1][e] * wg[1][e] + xg[2][e] * wg[2][e];
;                 const float cv_ = bv[e] + xv[0][e] * wv[0][e] + xv[1][e] * wv[1][e] + xv[2][e] * wv[2][e]; f[e] = gelu_tanh(cg_) * cv_; }
;             *(u32x4*)(F + (size_t)row * DFF + j0) = pack8(f);
.Lffn_r5_t1d:
	v_fmac_f32_e32 v144, v160, v16
	v_fmac_f32_e32 v152, v168, v24
	v_fmac_f32_e32 v145, v161, v17
	v_fmac_f32_e32 v153, v169, v25
	v_fmac_f32_e32 v146, v162, v18
	v_fmac_f32_e32 v154, v170, v26
	v_fmac_f32_e32 v147, v163, v19
	v_fmac_f32_e32 v155, v171, v27
	v_fmac_f32_e32 v148, v164, v20
	v_fmac_f32_e32 v156, v172, v28
	v_fmac_f32_e32 v149, v165, v21
	v_fmac_f32_e32 v157, v173, v29
	v_fmac_f32_e32 v150, v166, v22
	v_fmac_f32_e32 v158, v174, v30
	v_fmac_f32_e32 v151, v167, v23
	v_fmac_f32_e32 v159, v175, v31
	v_lshlrev_b32_e32 v160, 16, v104
	v_and_b32_e32 v161, 0xffff0000, v104
	v_lshlrev_b32_e32 v168, 16, v108
	v_and_b32_e32 v169, 0xffff0000, v108
	v_lshlrev_b32_e32 v162, 16, v105
	v_and_b32_e32 v163, 0xffff0000, v105
	v_lshlrev_b32_e32 v170, 16, v109
	v_and_b32_e32 v171, 0xffff0000, v109
	v_lshlrev_b32_e32 v164, 16, v106
	v_and_b32_e32 v165, 0xffff0000, v106
	v_lshlrev_b32_e32 v172, 16, v110
	v_and_b32_e32 v173, 0xffff0000, v110
	v_lshlrev_b32_e32 v166, 16, v107
	v_and_b32_e32 v167, 0xffff0000, v107
	v_lshlrev_b32_e32 v174, 16, v111
	v_and_b32_e32 v175, 0xffff0000, v111
	v_fmac_f32_e32 v144, v160, v32
	v_fmac_f32_e32 v152, v168, v40
	v_fmac_f32_e32 v145, v161, v33
	v_fmac_f32_e32 v153, v169, v41
	v_fmac_f32_e32 v146, v162, v34
	v_fmac_f32_e32 v154, v170, v42
	v_fmac_f32_e32 v147, v163, v35
	v_fmac_f32_e32 v155, v171, v43
	v_fmac_f32_e32 v148, v164, v36
	v_fmac_f32_e32 v156, v172, v44
	v_fmac_f32_e32 v149, v165, v37
	v_fmac_f32_e32 v157, v173, v45
	v_fmac_f32_e32 v150, v166, v38
	v_fmac_f32_e32 v158, v174, v46
	v_fmac_f32_e32 v151, v167, v39
	v_fmac_f32_e32 v159, v175, v47
	v_mul_f32_e32 v176, 0x3d372713, v144
	v_mul_f32_e32 v177, 0x3d372713, v145
	v_mul_f32_e32 v178, 0x3d372713, v146
	v_mul_f32_e32 v179, 0x3d372713, v147
	v_mul_f32_e32 v176, v144, v176
	v_mul_f32_e32 v177, v145, v177
	v_mul_f32_e32 v178, v146, v178
	v_mul_f32_e32 v179, v147, v179
	v_fma_f32 v176, v144, v176, v144
	v_fma_f32 v177, v145, v177, v145
	v_fma_f32 v178, v146, v178, v146
	v_fma_f32 v179, v147, v179, v147
	v_mul_f32_e32 v176, 0xbfcc422a, v176
	v_mul_f32_e32 v177, 0xbfcc422a, v177
	v_mul_f32_e32 v178, 0xbfcc422a, v178
	v_mul_f32_e32 v179, 0xbfcc422a, v179
	v_mul_f32_e32 v176, 0x3fb8aa3b, v176
	v_mul_f32_e32 v177, 0x3fb8aa3b, v177
	v_mul_f32_e32 v178, 0x3fb8aa3b, v178
	v_mul_f32_e32 v179, 0x3fb8aa3b, v179
	v_exp_f32_e32 v176, v176
	v_exp_f32_e32 v177, v177
	v_exp_f32_e32 v178, v178
	v_exp_f32_e32 v179, v179
	v_add_f32_e32 v176, 1.0, v176
	v_add_f32_e32 v177, 1.0, v177
	v_add_f32_e32 v178, 1.0, v178
	v_add_f32_e32 v179, 1.0, v179
	v_rcp_f32_e32 v176, v176
	v_rcp_f32_e32 v177, v177
	v_rcp_f32_e32 v178, v178
	v_rcp_f32_e32 v179, v179
	v_mul_f32_e32 v176, v144, v176
	v_mul_f32_e32 v177, v145, v177
	v_mul_f32_e32 v178, v146, v178
	v_mul_f32_e32 v179, v147, v179
	v_mul_f32_e32 v144, v176, v152
	v_mul_f32_e32 v145, v177, v153
	v_mul_f32_e32 v146, v178, v154
	v_mul_f32_e32 v147, v179, v155
	v_mul_f32_e32 v176, 0x3d372713, v148
	v_mul_f32_e32 v177, 0x3d372713, v149
	v_mul_f32_e32 v178, 0x3d372713, v150
	v_mul_f32_e32 v179, 0x3d372713, v151
	v_mul_f32_e32 v176, v148, v176
	v_mul_f32_e32 v177, v149, v177
	v_mul_f32_e32 v178, v150, v178
	v_mul_f32_e32 v179, v151, v179
	v_fma_f32 v176, v148, v176, v148
	v_fma_f32 v177, v149, v177, v149
	v_fma_f32 v178, v150, v178, v150
	v_fma_f32 v179, v151, v179, v151
	v_mul_f32_e32 v176, 0xbfcc422a, v176
	v_mul_f32_e32 v177, 0xbfcc422a, v177
	v_mul_f32_e32 v178, 0xbfcc422a, v178
	v_mul_f32_e32 v179, 0xbfcc422a, v179
	v_mul_f32_e32 v176, 0x3fb8aa3b, v176
	v_mul_f32_e32 v177, 0x3fb8aa3b, v177
	v_mul_f32_e32 v178, 0x3fb8aa3b, v178
	v_mul_f32_e32 v179, 0x3fb8aa3b, v179
	v_exp_f32_e32 v176, v176
	v_exp_f32_e32 v177, v177
	v_exp_f32_e32 v178, v178
	v_exp_f32_e32 v179, v179
	v_add_f32_e32 v176, 1.0, v176
	v_add_f32_e32 v177, 1.0, v177
	v_add_f32_e32 v178, 1.0, v178
	v_add_f32_e32 v179, 1.0, v179
	v_rcp_f32_e32 v176, v176
	v_rcp_f32_e32 v177, v177
	v_rcp_f32_e32 v178, v178
	v_rcp_f32_e32 v179, v179
	v_mul_f32_e32 v176, v148, v176
	v_mul_f32_e32 v177, v149, v177
	v_mul_f32_e32 v178, v150, v178
	v_mul_f32_e32 v179, v151, v179
	v_mul_f32_e32 v148, v176, v156
	v_mul_f32_e32 v149, v177, v157
	v_mul_f32_e32 v150, v178, v158
	v_mul_f32_e32 v151, v179, v159
	v_cvt_pk_bf16_f32 v180, v144, v145
	v_cvt_pk_bf16_f32 v181, v146, v147
	v_cvt_pk_bf16_f32 v182, v148, v149
	v_cvt_pk_bf16_f32 v183, v150, v151
	global_store_dwordx4 v189, v[180:183], s[26:27]
	s_add_i32 s35, s14, 1020
	s_cmp_ge_u32 s35, 0x400
	s_cbranch_scc1 .Lffn_done
	s_mov_b32 s29, 0
	s_cmp_eq_u32 s29, 0
	s_cbranch_scc1 .Lffn_r6_w0
	s_cmp_eq_u32 s29, 6
	s_cbranch_scc1 .Lffn_r6_w6
	s_cmp_eq_u32 s29, 10
	s_cbranch_scc1 .Lffn_r6_w10
	s_waitcnt vmcnt(15)
	s_branch .Lffn_r6_wd

; __device__ __forceinline__ void phase_ffnconv(const Params& p) {
;     ...
;             for (int k = 0; k < 3; ++k) { const int tt = t - 2 + k;
;                 if (tt >= 0) { unpack8(*(const u32x4*)(UP + (size_t)(row - 2 + k) * 2 * DFF + colg), xg[k]); unpack8(*(const u32x4*)(UP + (size_t)(row - 2 + k) * 2 * DFF + colg + 128), xv[k]); }
;                 else { const float* sp = p.in[I_SFCONV] + ((size_t)b * 2 + (2 + tt)) * 2 * DFF; ld8f(sp + j0, xg[k]); ld8f(sp + DFF + j0, xv[k]); } }
.Lffn_r6_wd:
	s_add_i32 s35, s14, 1020
	s_and_b32 s30, s35, 7
	s_mul_i32 s28, s35, 0x3000
	s_add_u32 s26, s6, s28
	s_addc_u32 s27, s7, 0
	s_cmp_gt_u32 s30, 1
	s_cbranch_scc1 .Lffn_r6_t0up
	v_mov_b32_e32 v160, v112
	v_mov_b32_e32 v168, v120
	v_mov_b32_e32 v161, v113
	v_mov_b32_e32 v169, v121
	v_mov_b32_e32 v162, v114
	v_mov_b32_e32 v170, v122
	v_mov_b32_e32 v163, v115
	v_mov_b32_e32 v171, v123
	v_mov_b32_e32 v164, v116
	v_mov_b32_e32 v172, v124
	v_mov_b32_e32 v165, v117
	v_mov_b32_e32 v173, v125
	v_mov_b32_e32 v166, v118
	v_mov_b32_e32 v174, v126
	v_mov_b32_e32 v167, v119
	v_mov_b32_e32 v175, v127
	s_branch .Lffn_r6_t0d

; __device__ __forceinline__ u32x4 pack8(const float (&f)[8]) { u32x4 w; w.x = pk2(f[0], f[1]); w.y = pk2(f[2], f[3]); w.z = pk2(f[4], f[5]); w.w = pk2(f[6], f[7]); return w; }
; __device__ __forceinline__ float gelu_tanh(float x) { const float y = 1.5957691216f * (x + 0.044715f * x * x * x); return x * __builtin_amdgcn_rcpf(1.0f + __expf(-y)); }
; __device__ __forceinline__ void phase_ffnconv(const Params& p) {
;     ...
;             for (int k = 0; k < 3; ++k) { const int tt = t - 2 + k;
;                 if (tt >= 0) { unpack8(*(const u32x4*)(UP + (size_t)(row - 2 + k) * 2 * DFF + colg), xg[k]); unpack8(*(const u32x4*)(UP + (size_t)(row - 2 + k) * 2 * DFF + colg + 128), xv[k]); }
;                 else { const float* sp = p.in[I_SFCONV] + ((size_t)b * 2 + (2 + tt)) * 2 * DFF; ld8f(sp + j0, xg[k]); ld8f(sp + DFF + j0, xv[k]); } }
;             float f[8];
; #pragma unroll
;             for (int e = 0; e < 8; ++e) { const float cg_ = bg[e] + xg[0][e] * wg[0][e] + xg[1][e] * wg[1][e] + xg[2][e] * wg[2][e];
;                 const float cv_ = bv[e] + xv[0][e] * wv[0][e] + xv[1][e] * wv[1][e] + xv[2][e] * wv[2][e]; f[e] = gelu_tanh(cg_) * cv_; }
;             *(u32x4*)(F + (size_t)row * DFF + j0) = pack8(f);
.Lffn_r6_t1d:
	v_fmac_f32_e32 v144, v160, v16
	v_fmac_f32_e32 v152, v168, v24
	v_fmac_f32_e32 v145, v161, v17
	v_fmac_f32_e32 v153, v169, v25
	v_fmac_f32_e32 v146, v162, v18
	v_fmac_f32_e32 v154, v170, v26
	v_fmac_f32_e32 v147, v163, v19
	v_fmac_f32_e32 v155, v171, v27
	v_fmac_f32_e32 v148, v164, v20
	v_fmac_f32_e32 v156, v172, v28
	v_fmac_f32_e32 v149, v165, v21
	v_fmac_f32_e32 v157, v173, v29
	v_fmac_f32_e32 v150, v166, v22
	v_fmac_f32_e32 v158, v174, v30
	v_fmac_f32_e32 v151, v167, v23
	v_fmac_f32_e32 v159, v175, v31
	v_lshlrev_b32_e32 v160, 16, v80
	v_and_b32_e32 v161, 0xffff0000, v80
	v_lshlrev_b32_e32 v168, 16, v84
	v_and_b32_e32 v169, 0xffff0000, v84
	v_lshlrev_b32_e32 v162, 16, v81
	v_and_b32_e32 v163, 0xffff0000, v81
	v_lshlrev_b32_e32 v170, 16, v85
	v_and_b32_e32 v171, 0xffff0000, v85
	v_lshlrev_b32_e32 v164, 16, v82
	v_and_b32_e32 v165, 0xffff0000, v82
	v_lshlrev_b32_e32 v172, 16, v86
	v_and_b32_e32 v173, 0xffff0000, v86
	v_lshlrev_b32_e32 v166, 16, v83
	v_and_b32_e32 v167, 0xffff0000, v83
	v_lshlrev_b32_e32 v174, 16, v87
	v_and_b32_e32 v175, 0xffff0000, v87
	v_fmac_f32_e32 v144, v160, v32
	v_fmac_f32_e32 v152, v168, v40
	v_fmac_f32_e32 v145, v161, v33
	v_fmac_f32_e32 v153, v169, v41
	v_fmac_f32_e32 v146, v162, v34
	v_fmac_f32_e32 v154, v170, v42
	v_fmac_f32_e32 v147, v163, v35
	v_fmac_f32_e32 v155, v171, v43
	v_fmac_f32_e32 v148, v164, v36
	v_fmac_f32_e32 v156, v172, v44
	v_fmac_f32_e32 v149, v165, v37
	v_fmac_f32_e32 v157, v173, v45
	v_fmac_f32_e32 v150, v166, v38
	v_fmac_f32_e32 v158, v174, v46
	v_fmac_f32_e32 v151, v167, v39
	v_fmac_f32_e32 v159, v175, v47
	v_mul_f32_e32 v176, 0x3d372713, v144
	v_mul_f32_e32 v177, 0x3d372713, v145
	v_mul_f32_e32 v178, 0x3d372713, v146
	v_mul_f32_e32 v179, 0x3d372713, v147
	v_mul_f32_e32 v176, v144, v176
	v_mul_f32_e32 v177, v145, v177
	v_mul_f32_e32 v178, v146, v178
	v_mul_f32_e32 v179, v147, v179
	v_fma_f32 v176, v144, v176, v144
	v_fma_f32 v177, v145, v177, v145
	v_fma_f32 v178, v146, v178, v146
	v_fma_f32 v179, v147, v179, v147
	v_mul_f32_e32 v176, 0xbfcc422a, v176
	v_mul_f32_e32 v177, 0xbfcc422a, v177
	v_mul_f32_e32 v178, 0xbfcc422a, v178
	v_mul_f32_e32 v179, 0xbfcc422a, v179
	v_mul_f32_e32 v176, 0x3fb8aa3b, v176
	v_mul_f32_e32 v177, 0x3fb8aa3b, v177
	v_mul_f32_e32 v178, 0x3fb8aa3b, v178
	v_mul_f32_e32 v179, 0x3fb8aa3b, v179
	v_exp_f32_e32 v176, v176
	v_exp_f32_e32 v177, v177
	v_exp_f32_e32 v178, v178
	v_exp_f32_e32 v179, v179
	v_add_f32_e32 v176, 1.0, v176
	v_add_f32_e32 v177, 1.0, v177
	v_add_f32_e32 v178, 1.0, v178
	v_add_f32_e32 v179, 1.0, v179
	v_rcp_f32_e32 v176, v176
	v_rcp_f32_e32 v177, v177
	v_rcp_f32_e32 v178, v178
	v_rcp_f32_e32 v179, v179
	v_mul_f32_e32 v176, v144, v176
	v_mul_f32_e32 v177, v145, v177
	v_mul_f32_e32 v178, v146, v178
	v_mul_f32_e32 v179, v147, v179
	v_mul_f32_e32 v144, v176, v152
	v_mul_f32_e32 v145, v177, v153
	v_mul_f32_e32 v146, v178, v154
	v_mul_f32_e32 v147, v179, v155
	v_mul_f32_e32 v176, 0x3d372713, v148
	v_mul_f32_e32 v177, 0x3d372713, v149
	v_mul_f32_e32 v178, 0x3d372713, v150
	v_mul_f32_e32 v179, 0x3d372713, v151
	v_mul_f32_e32 v176, v148, v176
	v_mul_f32_e32 v177, v149, v177
	v_mul_f32_e32 v178, v150, v178
	v_mul_f32_e32 v179, v151, v179
	v_fma_f32 v176, v148, v176, v148
	v_fma_f32 v177, v149, v177, v149
	v_fma_f32 v178, v150, v178, v150
	v_fma_f32 v179, v151, v179, v151
	v_mul_f32_e32 v176, 0xbfcc422a, v176
	v_mul_f32_e32 v177, 0xbfcc422a, v177
	v_mul_f32_e32 v178, 0xbfcc422a, v178
	v_mul_f32_e32 v179, 0xbfcc422a, v179
	v_mul_f32_e32 v176, 0x3fb8aa3b, v176
	v_mul_f32_e32 v177, 0x3fb8aa3b, v177
	v_mul_f32_e32 v178, 0x3fb8aa3b, v178
	v_mul_f32_e32 v179, 0x3fb8aa3b, v179
	v_exp_f32_e32 v176, v176
	v_exp_f32_e32 v177, v177
	v_exp_f32_e32 v178, v178
	v_exp_f32_e32 v179, v179
	v_add_f32_e32 v176, 1.0, v176
	v_add_f32_e32 v177, 1.0, v177
	v_add_f32_e32 v178, 1.0, v178
	v_add_f32_e32 v179, 1.0, v179
	v_rcp_f32_e32 v176, v176
	v_rcp_f32_e32 v177, v177
	v_rcp_f32_e32 v178, v178
	v_rcp_f32_e32 v179, v179
	v_mul_f32_e32 v176, v148, v176
	v_mul_f32_e32 v177, v149, v177
	v_mul_f32_e32 v178, v150, v178
	v_mul_f32_e32 v179, v151, v179
	v_mul_f32_e32 v148, v176, v156
	v_mul_f32_e32 v149, v177, v157
	v_mul_f32_e32 v150, v178, v158
	v_mul_f32_e32 v151, v179, v159
	v_cvt_pk_bf16_f32 v180, v144, v145
	v_cvt_pk_bf16_f32 v181, v146, v147
	v_cvt_pk_bf16_f32 v182, v148, v149
	v_cvt_pk_bf16_f32 v183, v150, v151
	global_store_dwordx4 v189, v[180:183], s[26:27]
.Lffn_done:
	s_mov_b64 s[6:7], exec
